# removed the lgkmcnt(8) pacing wait in front of the first barrier of GEMM phases 1 and 5 (all five K-loops); the lgkmcnt(0) after the barrier still guards the MFMA operands
# speedup vs baseline: 1.0038x; 1.0038x over previous
; #define PG8_STAGE(bufoff, gbase, voff) do { _Pragma("unroll") for (int _i = 0; _i < 2; ++_i) \
;     __builtin_amdgcn_global_load_lds((const unsigned*)((const char*)(gbase) + (voff)[_i]), (PG8_LAS unsigned*)(lds + (bufoff) + ldsw + _i * 8192), 16, 0, 0); } while (0)
; #define PG8_LDA(dst, b, h) do { _Pragma("unroll") for (int m = 0; m < 4; ++m) _Pragma("unroll") for (int k = 0; k < 2; ++k) dst[m][k] = *(const PG8_LAS bf16x8*)(lds + PG8_SA(b, h) + aoff + m * 2048 + k * 1024); } while (0)
; #define PG8_LDB(dst, b, h) do { _Pragma("unroll") for (int n = 0; n < 2; ++n) _Pragma("unroll") for (int k = 0; k < 2; ++k) dst[n][k] = *(const PG8_LAS bf16x8*)(lds + PG8_SB(b, h) + boff + n * 2048 + k * 1024); } while (0)
; #define PG8_MMA(ai, bj, At, Bt) do { __builtin_amdgcn_s_setprio(1); _Pragma("unroll") for (int m = 0; m < 4; ++m) _Pragma("unroll") for (int n = 0; n < 2; ++n) _Pragma("unroll") for (int k = 0; k < 2; ++k) \
;     acc[ai][bj][m][n] = __builtin_amdgcn_mfma_f32_16x16x32_bf16(Bt[n][k], At[m][k], acc[ai][bj][m][n], 0, 0, 0); __builtin_amdgcn_s_setprio(0); } while (0)
; #define PG8_WAIT_V(n) asm volatile("s_waitcnt vmcnt(" #n ")" ::: "memory")
; #define PG8_WAIT_L(n) asm volatile("s_waitcnt lgkmcnt(" #n ")" ::: "memory")
; #define PG8_BAR __builtin_amdgcn_s_barrier()
; template <class Epi>
; DI void gemm_phase(const bf16_t* __restrict__ gA, const bf16_t* __restrict__ gBt, int M, int N, int K, const Epi& E, char* lds_generic) {
;     ...
;     for (int t = 0; t < nt; t += 2) {
;       const bool last = (t == nt - 2);
;       const char* a1 = cA + (size_t)(t + 1) * kstep;
;       const char* a2 = last ? nA : cA + (size_t)(t + 2) * kstep; const char* b2 = last ? nB : cB + (size_t)(t + 2) * kstep;
;       const char* a3 = a2 + kstep; const char* b3 = b2 + kstep;
;       PG8_LDB(B0, 0, 0); PG8_SCHED; PG8_LDA(At, 0, 0); PG8_STAGE(PG8_SA(1, 1), a1 + hstep, voffA);
;       PG8_WAIT_L(8); PG8_BAR; PG8_WAIT_L(0); PG8_MMA(0, 0, At, B0); PG8_BAR; PG8_SCHED;
;       PG8_LDB(B1, 0, 1); PG8_STAGE(PG8_SB(0, 0), b2, voffB);
;       PG8_BAR; PG8_WAIT_L(0); PG8_MMA(0, 1, At, B1); PG8_BAR;
;       PG8_LDA(At, 0, 1); PG8_STAGE(PG8_SA(0, 0), a2, voffA);
;       PG8_BAR; PG8_WAIT_L(0); PG8_MMA(1, 0, At, B0); PG8_BAR; PG8_SCHED;
;       PG8_STAGE(PG8_SB(0, 1), b2 + hstep, voffB);
;       PG8_WAIT_V(6); PG8_BAR; PG8_MMA(1, 1, At, B1); PG8_BAR;
.LBB0_137:
	ds_read_b128 v[130:133], v157
	ds_read_b128 v[146:149], v158
	ds_read_b128 v[176:179], v159
	ds_read_b128 v[180:183], v160
	s_add_u32 s24, s80, 0xfffc0080
	s_addc_u32 s25, s81, -1
	s_cmp_eq_u32 s62, 12
	s_cselect_b32 s31, s22, s25
	s_cselect_b32 s30, s23, s24
	s_cselect_b32 s29, s1, s61
	s_cselect_b32 s28, s27, s60
	s_mov_b32 m0, s33
	v_lshl_add_u64 v[216:217], s[80:81], 0, v[142:143]
	ds_read_b128 v[184:187], v154
	ds_read_b128 v[188:191], v154 offset:1024
	ds_read_b128 v[192:195], v154 offset:2048
	ds_read_b128 v[196:199], v154 offset:3072
	ds_read_b128 v[200:203], v154 offset:4096
	ds_read_b128 v[204:207], v154 offset:5120
	ds_read_b128 v[208:211], v154 offset:6144
	ds_read_b128 v[212:215], v154 offset:7168
	global_load_lds_dwordx4 v[216:217], off
	v_lshl_add_u64 v[216:217], s[80:81], 0, v[144:145]
	s_mov_b32 m0, s35
	s_nop 0
	global_load_lds_dwordx4 v[216:217], off
	s_barrier
	s_waitcnt lgkmcnt(0)
	s_waitcnt lgkmcnt(0)
	v_mfma_f32_16x16x32_bf16 v[126:129], v[130:133], v[184:187], v[126:129]
	v_mfma_f32_16x16x32_bf16 v[122:125], v[176:179], v[184:187], v[122:125]
	v_mfma_f32_16x16x32_bf16 v[118:121], v[130:133], v[192:195], v[118:121]
	v_mfma_f32_16x16x32_bf16 v[110:113], v[176:179], v[192:195], v[110:113]
	v_mfma_f32_16x16x32_bf16 v[98:101], v[130:133], v[200:203], v[98:101]
	v_mfma_f32_16x16x32_bf16 v[90:93], v[176:179], v[200:203], v[90:93]
	v_mfma_f32_16x16x32_bf16 v[86:89], v[130:133], v[208:211], v[86:89]
	v_mfma_f32_16x16x32_bf16 v[78:81], v[176:179], v[208:211], v[78:81]
	v_mfma_f32_16x16x32_bf16 v[126:129], v[146:149], v[188:191], v[126:129]
	v_mfma_f32_16x16x32_bf16 v[122:125], v[180:183], v[188:191], v[122:125]
	v_mfma_f32_16x16x32_bf16 v[118:121], v[146:149], v[196:199], v[118:121]
	v_mfma_f32_16x16x32_bf16 v[110:113], v[180:183], v[196:199], v[110:113]
	v_mfma_f32_16x16x32_bf16 v[98:101], v[146:149], v[204:207], v[98:101]
	v_mfma_f32_16x16x32_bf16 v[90:93], v[180:183], v[204:207], v[90:93]
	v_mfma_f32_16x16x32_bf16 v[86:89], v[146:149], v[212:215], v[86:89]
	v_mfma_f32_16x16x32_bf16 v[78:81], v[180:183], v[212:215], v[78:81]
	s_barrier
	s_mov_b32 m0, s6
	v_lshl_add_u64 v[220:221], s[28:29], 0, v[0:1]
	ds_read_b128 v[216:219], v161
	ds_read_b128 v[238:241], v163
	ds_read_b128 v[242:245], v165
	ds_read_b128 v[246:249], v166
	global_load_lds_dwordx4 v[220:221], off
	v_lshl_add_u64 v[250:251], s[28:29], 0, v[138:139]
	s_mov_b32 m0, s7
	s_nop 0
	global_load_lds_dwordx4 v[250:251], off
	s_barrier
	s_waitcnt lgkmcnt(0)
	s_waitcnt lgkmcnt(0)
	v_mfma_f32_16x16x32_bf16 v[114:117], v[216:219], v[184:187], v[114:117]
	v_mfma_f32_16x16x32_bf16 v[106:109], v[242:245], v[184:187], v[106:109]
	v_mfma_f32_16x16x32_bf16 v[102:105], v[216:219], v[192:195], v[102:105]
	v_mfma_f32_16x16x32_bf16 v[94:97], v[242:245], v[192:195], v[94:97]
	v_mfma_f32_16x16x32_bf16 v[82:85], v[216:219], v[200:203], v[82:85]
	v_mfma_f32_16x16x32_bf16 v[74:77], v[242:245], v[200:203], v[74:77]
	v_mfma_f32_16x16x32_bf16 v[70:73], v[216:219], v[208:211], v[70:73]
	v_mfma_f32_16x16x32_bf16 v[66:69], v[242:245], v[208:211], v[66:69]
	v_mfma_f32_16x16x32_bf16 v[114:117], v[238:241], v[188:191], v[114:117]
	v_mfma_f32_16x16x32_bf16 v[106:109], v[246:249], v[188:191], v[106:109]
	v_mfma_f32_16x16x32_bf16 v[102:105], v[238:241], v[196:199], v[102:105]
	v_mfma_f32_16x16x32_bf16 v[94:97], v[246:249], v[196:199], v[94:97]
	v_mfma_f32_16x16x32_bf16 v[82:85], v[238:241], v[204:207], v[82:85]
	v_mfma_f32_16x16x32_bf16 v[74:77], v[246:249], v[204:207], v[74:77]
	v_mfma_f32_16x16x32_bf16 v[70:73], v[238:241], v[212:215], v[70:73]
	v_mfma_f32_16x16x32_bf16 v[66:69], v[246:249], v[212:215], v[66:69]
	s_mov_b32 m0, s5
	v_lshl_add_u64 v[228:229], s[30:31], 0, v[134:135]
	s_barrier
	ds_read_b128 v[184:187], v154 offset:16384
	ds_read_b128 v[188:191], v154 offset:17408
	ds_read_b128 v[192:195], v154 offset:18432
	ds_read_b128 v[196:199], v154 offset:19456
	ds_read_b128 v[200:203], v154 offset:20480
	ds_read_b128 v[204:207], v154 offset:21504
	ds_read_b128 v[208:211], v154 offset:22528
	ds_read_b128 v[212:215], v154 offset:23552
	global_load_lds_dwordx4 v[228:229], off
	v_lshl_add_u64 v[226:227], s[30:31], 0, v[136:137]
	s_mov_b32 m0, s8
	s_nop 0
	global_load_lds_dwordx4 v[226:227], off
	s_barrier
	s_waitcnt lgkmcnt(0)
	s_waitcnt lgkmcnt(0)
	v_mfma_f32_16x16x32_bf16 v[62:65], v[130:133], v[184:187], v[62:65]
	v_mfma_f32_16x16x32_bf16 v[58:61], v[176:179], v[184:187], v[58:61]
	v_mfma_f32_16x16x32_bf16 v[54:57], v[130:133], v[192:195], v[54:57]
	v_mfma_f32_16x16x32_bf16 v[46:49], v[176:179], v[192:195], v[46:49]
	v_mfma_f32_16x16x32_bf16 v[34:37], v[130:133], v[200:203], v[34:37]
	v_mfma_f32_16x16x32_bf16 v[26:29], v[176:179], v[200:203], v[26:29]
	v_mfma_f32_16x16x32_bf16 v[22:25], v[130:133], v[208:211], v[22:25]
	v_mfma_f32_16x16x32_bf16 v[14:17], v[176:179], v[208:211], v[14:17]
	v_mfma_f32_16x16x32_bf16 v[62:65], v[146:149], v[188:191], v[62:65]
	v_mfma_f32_16x16x32_bf16 v[58:61], v[180:183], v[188:191], v[58:61]
	v_mfma_f32_16x16x32_bf16 v[54:57], v[146:149], v[196:199], v[54:57]
	v_mfma_f32_16x16x32_bf16 v[46:49], v[180:183], v[196:199], v[46:49]
	v_mfma_f32_16x16x32_bf16 v[34:37], v[146:149], v[204:207], v[34:37]
	v_mfma_f32_16x16x32_bf16 v[26:29], v[180:183], v[204:207], v[26:29]
	v_mfma_f32_16x16x32_bf16 v[22:25], v[146:149], v[212:215], v[22:25]
	v_mfma_f32_16x16x32_bf16 v[14:17], v[180:183], v[212:215], v[14:17]
	s_barrier
	s_add_u32 s82, s28, 0x40000
	s_addc_u32 s83, s29, 0
	s_mov_b32 m0, s9
	v_lshl_add_u64 v[130:131], s[82:83], 0, v[0:1]
	global_load_lds_dwordx4 v[130:131], off
	v_lshl_add_u64 v[130:131], s[82:83], 0, v[138:139]
	s_mov_b32 m0, s12
	s_nop 0
	global_load_lds_dwordx4 v[130:131], off
	s_waitcnt vmcnt(6)
	s_barrier
; #define PG8_STAGE(bufoff, gbase, voff) do { _Pragma("unroll") for (int _i = 0; _i < 2; ++_i) \
;     __builtin_amdgcn_global_load_lds((const unsigned*)((const char*)(gbase) + (voff)[_i]), (PG8_LAS unsigned*)(lds + (bufoff) + ldsw + _i * 8192), 16, 0, 0); } while (0)
; #define PG8_LDA(dst, b, h) do { _Pragma("unroll") for (int m = 0; m < 4; ++m) _Pragma("unroll") for (int k = 0; k < 2; ++k) dst[m][k] = *(const PG8_LAS bf16x8*)(lds + PG8_SA(b, h) + aoff + m * 2048 + k * 1024); } while (0)
; #define PG8_LDB(dst, b, h) do { _Pragma("unroll") for (int n = 0; n < 2; ++n) _Pragma("unroll") for (int k = 0; k < 2; ++k) dst[n][k] = *(const PG8_LAS bf16x8*)(lds + PG8_SB(b, h) + boff + n * 2048 + k * 1024); } while (0)
; #define PG8_MMA(ai, bj, At, Bt) do { __builtin_amdgcn_s_setprio(1); _Pragma("unroll") for (int m = 0; m < 4; ++m) _Pragma("unroll") for (int n = 0; n < 2; ++n) _Pragma("unroll") for (int k = 0; k < 2; ++k) \
;     acc[ai][bj][m][n] = __builtin_amdgcn_mfma_f32_16x16x32_bf16(Bt[n][k], At[m][k], acc[ai][bj][m][n], 0, 0, 0); __builtin_amdgcn_s_setprio(0); } while (0)
; #define PG8_WAIT_V(n) asm volatile("s_waitcnt vmcnt(" #n ")" ::: "memory")
; #define PG8_WAIT_L(n) asm volatile("s_waitcnt lgkmcnt(" #n ")" ::: "memory")
; #define PG8_BAR __builtin_amdgcn_s_barrier()
; #define PG8_SCHED __builtin_amdgcn_sched_barrier(0)
; template <class Epi>
; DI void gemm_phase(const bf16_t* __restrict__ gA, const bf16_t* __restrict__ gBt, int M, int N, int K, const Epi& E, char* lds_generic) {
;     ...
;       PG8_WAIT_V(6); PG8_BAR; PG8_MMA(1, 1, At, B1); PG8_BAR;
;       PG8_LDB(B0, 1, 0); PG8_SCHED; PG8_LDA(At, 1, 0); PG8_STAGE(PG8_SA(0, 1), a2 + hstep, voffA);
;       PG8_WAIT_L(8); PG8_BAR; PG8_WAIT_L(0); PG8_MMA(0, 0, At, B0); PG8_BAR; PG8_SCHED;
;       PG8_LDB(B1, 1, 1); PG8_STAGE(PG8_SB(1, 0), b3, voffB);
;       PG8_BAR; PG8_WAIT_L(0); PG8_MMA(0, 1, At, B1); PG8_BAR;
	v_mfma_f32_16x16x32_bf16 v[50:53], v[216:219], v[184:187], v[50:53]
	v_mfma_f32_16x16x32_bf16 v[42:45], v[242:245], v[184:187], v[42:45]
	v_mfma_f32_16x16x32_bf16 v[38:41], v[216:219], v[192:195], v[38:41]
	v_mfma_f32_16x16x32_bf16 v[30:33], v[242:245], v[192:195], v[30:33]
	v_mfma_f32_16x16x32_bf16 v[18:21], v[216:219], v[200:203], v[18:21]
	v_mfma_f32_16x16x32_bf16 v[10:13], v[242:245], v[200:203], v[10:13]
	v_mfma_f32_16x16x32_bf16 v[6:9], v[216:219], v[208:211], v[6:9]
	v_mfma_f32_16x16x32_bf16 v[2:5], v[242:245], v[208:211], v[2:5]
	v_mfma_f32_16x16x32_bf16 v[50:53], v[238:241], v[188:191], v[50:53]
	v_mfma_f32_16x16x32_bf16 v[42:45], v[246:249], v[188:191], v[42:45]
	v_mfma_f32_16x16x32_bf16 v[38:41], v[238:241], v[196:199], v[38:41]
	v_mfma_f32_16x16x32_bf16 v[30:33], v[246:249], v[196:199], v[30:33]
	v_mfma_f32_16x16x32_bf16 v[18:21], v[238:241], v[204:207], v[18:21]
	v_mfma_f32_16x16x32_bf16 v[10:13], v[246:249], v[204:207], v[10:13]
	v_mfma_f32_16x16x32_bf16 v[6:9], v[238:241], v[212:215], v[6:9]
	v_mfma_f32_16x16x32_bf16 v[2:5], v[246:249], v[212:215], v[2:5]
	s_barrier
	ds_read_b128 v[130:133], v167
	ds_read_b128 v[146:149], v168
	ds_read_b128 v[176:179], v169
	ds_read_b128 v[180:183], v170
	s_add_u32 s30, s30, 0x40000
	s_addc_u32 s31, s31, 0
	s_mov_b32 m0, s13
	v_lshl_add_u64 v[216:217], s[30:31], 0, v[134:135]
	ds_read_b128 v[184:187], v154 offset:32768
	ds_read_b128 v[188:191], v154 offset:33792
	ds_read_b128 v[192:195], v154 offset:34816
	ds_read_b128 v[196:199], v154 offset:35840
	ds_read_b128 v[200:203], v154 offset:36864
	ds_read_b128 v[204:207], v154 offset:37888
	ds_read_b128 v[208:211], v154 offset:38912
	ds_read_b128 v[212:215], v154 offset:39936
	global_load_lds_dwordx4 v[216:217], off
	v_lshl_add_u64 v[216:217], s[30:31], 0, v[136:137]
	s_mov_b32 m0, s14
	s_nop 0
	global_load_lds_dwordx4 v[216:217], off
	s_barrier
	s_waitcnt lgkmcnt(0)
	s_waitcnt lgkmcnt(0)
	v_mfma_f32_16x16x32_bf16 v[126:129], v[130:133], v[184:187], v[126:129]
	v_mfma_f32_16x16x32_bf16 v[122:125], v[176:179], v[184:187], v[122:125]
	v_mfma_f32_16x16x32_bf16 v[118:121], v[130:133], v[192:195], v[118:121]
	v_mfma_f32_16x16x32_bf16 v[110:113], v[176:179], v[192:195], v[110:113]
	v_mfma_f32_16x16x32_bf16 v[98:101], v[130:133], v[200:203], v[98:101]
	v_mfma_f32_16x16x32_bf16 v[90:93], v[176:179], v[200:203], v[90:93]
	v_mfma_f32_16x16x32_bf16 v[86:89], v[130:133], v[208:211], v[86:89]
	v_mfma_f32_16x16x32_bf16 v[78:81], v[176:179], v[208:211], v[78:81]
	v_mfma_f32_16x16x32_bf16 v[126:129], v[146:149], v[188:191], v[126:129]
	v_mfma_f32_16x16x32_bf16 v[122:125], v[180:183], v[188:191], v[122:125]
	v_mfma_f32_16x16x32_bf16 v[118:121], v[146:149], v[196:199], v[118:121]
	v_mfma_f32_16x16x32_bf16 v[110:113], v[180:183], v[196:199], v[110:113]
	v_mfma_f32_16x16x32_bf16 v[98:101], v[146:149], v[204:207], v[98:101]
	v_mfma_f32_16x16x32_bf16 v[90:93], v[180:183], v[204:207], v[90:93]
	v_mfma_f32_16x16x32_bf16 v[86:89], v[146:149], v[212:215], v[86:89]
	v_mfma_f32_16x16x32_bf16 v[78:81], v[180:183], v[212:215], v[78:81]
	s_barrier
	s_mov_b32 m0, s15
	v_lshl_add_u64 v[220:221], v[220:221], 0, s[10:11]
	ds_read_b128 v[216:219], v171
	ds_read_b128 v[238:241], v172
	ds_read_b128 v[242:245], v173
	ds_read_b128 v[246:249], v174
	global_load_lds_dwordx4 v[220:221], off
	v_lshl_add_u64 v[220:221], v[250:251], 0, s[10:11]
	s_mov_b32 m0, s16
	s_nop 0
	global_load_lds_dwordx4 v[220:221], off
	s_barrier
	s_waitcnt lgkmcnt(0)
	s_waitcnt lgkmcnt(0)
	v_mfma_f32_16x16x32_bf16 v[114:117], v[216:219], v[184:187], v[114:117]
	v_mfma_f32_16x16x32_bf16 v[106:109], v[242:245], v[184:187], v[106:109]
	v_mfma_f32_16x16x32_bf16 v[102:105], v[216:219], v[192:195], v[102:105]
	v_mfma_f32_16x16x32_bf16 v[94:97], v[242:245], v[192:195], v[94:97]
	v_mfma_f32_16x16x32_bf16 v[82:85], v[216:219], v[200:203], v[82:85]
	v_mfma_f32_16x16x32_bf16 v[74:77], v[242:245], v[200:203], v[74:77]
	v_mfma_f32_16x16x32_bf16 v[70:73], v[216:219], v[208:211], v[70:73]
	v_mfma_f32_16x16x32_bf16 v[66:69], v[242:245], v[208:211], v[66:69]
	v_mfma_f32_16x16x32_bf16 v[114:117], v[238:241], v[188:191], v[114:117]
	v_mfma_f32_16x16x32_bf16 v[106:109], v[246:249], v[188:191], v[106:109]
	v_mfma_f32_16x16x32_bf16 v[102:105], v[238:241], v[196:199], v[102:105]
	v_mfma_f32_16x16x32_bf16 v[94:97], v[246:249], v[196:199], v[94:97]
	v_mfma_f32_16x16x32_bf16 v[82:85], v[238:241], v[204:207], v[82:85]
	v_mfma_f32_16x16x32_bf16 v[74:77], v[246:249], v[204:207], v[74:77]
	v_mfma_f32_16x16x32_bf16 v[70:73], v[238:241], v[212:215], v[70:73]
	v_mfma_f32_16x16x32_bf16 v[66:69], v[246:249], v[212:215], v[66:69]
	s_mov_b32 m0, s18
	v_lshl_add_u64 v[220:221], v[228:229], 0, s[10:11]
	s_barrier
; #define PG8_STAGE(bufoff, gbase, voff) do { _Pragma("unroll") for (int _i = 0; _i < 2; ++_i) \
;     __builtin_amdgcn_global_load_lds((const unsigned*)((const char*)(gbase) + (voff)[_i]), (PG8_LAS unsigned*)(lds + (bufoff) + ldsw + _i * 8192), 16, 0, 0); } while (0)
; #define PG8_LDA(dst, b, h) do { _Pragma("unroll") for (int m = 0; m < 4; ++m) _Pragma("unroll") for (int k = 0; k < 2; ++k) dst[m][k] = *(const PG8_LAS bf16x8*)(lds + PG8_SA(b, h) + aoff + m * 2048 + k * 1024); } while (0)
; #define PG8_MMA(ai, bj, At, Bt) do { __builtin_amdgcn_s_setprio(1); _Pragma("unroll") for (int m = 0; m < 4; ++m) _Pragma("unroll") for (int n = 0; n < 2; ++n) _Pragma("unroll") for (int k = 0; k < 2; ++k) \
;     acc[ai][bj][m][n] = __builtin_amdgcn_mfma_f32_16x16x32_bf16(Bt[n][k], At[m][k], acc[ai][bj][m][n], 0, 0, 0); __builtin_amdgcn_s_setprio(0); } while (0)
; #define PG8_WAIT_V(n) asm volatile("s_waitcnt vmcnt(" #n ")" ::: "memory")
; #define PG8_WAIT_L(n) asm volatile("s_waitcnt lgkmcnt(" #n ")" ::: "memory")
; #define PG8_BAR __builtin_amdgcn_s_barrier()
; #define PG8_SCHED __builtin_amdgcn_sched_barrier(0)
; #define PG8_RTAB_LOAD(var, unit) do { if constexpr (Epi::NEEDS_R) { var = *(const uint4*)(E.ssq + (size_t)((unit).pm * BM + (tid >> 1)) * 16 + (tid & 1) * 8); } } while (0)
; template <class Epi>
; DI void gemm_phase(const bf16_t* __restrict__ gA, const bf16_t* __restrict__ gBt, int M, int N, int K, const Epi& E, char* lds_generic) {
;     ...
;       PG8_LDA(At, 1, 1); PG8_STAGE(PG8_SA(1, 0), a3, voffA);
;       PG8_BAR; PG8_WAIT_L(0); PG8_MMA(1, 0, At, B0); PG8_BAR; PG8_SCHED;
;       PG8_STAGE(PG8_SB(1, 1), b3 + hstep, voffB);
;       PG8_WAIT_V(6); PG8_BAR; PG8_MMA(1, 1, At, B1); PG8_BAR;
;     }
;     uint4 rtn_ = {0u, 0u, 0u, 0u};
;     if (has_next) PG8_RTAB_LOAD(rtn_, nxt);
	ds_read_b128 v[184:187], v154 offset:49152
	ds_read_b128 v[188:191], v154 offset:50176
	ds_read_b128 v[192:195], v154 offset:51200
	ds_read_b128 v[196:199], v154 offset:52224
	ds_read_b128 v[200:203], v154 offset:53248
	ds_read_b128 v[204:207], v154 offset:54272
	ds_read_b128 v[208:211], v154 offset:55296
	ds_read_b128 v[212:215], v154 offset:56320
	global_load_lds_dwordx4 v[220:221], off
	v_lshl_add_u64 v[220:221], v[226:227], 0, s[10:11]
	s_mov_b32 m0, s19
	s_nop 0
	global_load_lds_dwordx4 v[220:221], off
	s_barrier
	s_waitcnt lgkmcnt(0)
	s_waitcnt lgkmcnt(0)
	v_mfma_f32_16x16x32_bf16 v[62:65], v[130:133], v[184:187], v[62:65]
	v_mfma_f32_16x16x32_bf16 v[58:61], v[176:179], v[184:187], v[58:61]
	v_mfma_f32_16x16x32_bf16 v[54:57], v[130:133], v[192:195], v[54:57]
	v_mfma_f32_16x16x32_bf16 v[46:49], v[176:179], v[192:195], v[46:49]
	v_mfma_f32_16x16x32_bf16 v[34:37], v[130:133], v[200:203], v[34:37]
	v_mfma_f32_16x16x32_bf16 v[26:29], v[176:179], v[200:203], v[26:29]
	v_mfma_f32_16x16x32_bf16 v[22:25], v[130:133], v[208:211], v[22:25]
	v_mfma_f32_16x16x32_bf16 v[14:17], v[176:179], v[208:211], v[14:17]
	v_mfma_f32_16x16x32_bf16 v[62:65], v[146:149], v[188:191], v[62:65]
	v_mfma_f32_16x16x32_bf16 v[58:61], v[180:183], v[188:191], v[58:61]
	v_mfma_f32_16x16x32_bf16 v[54:57], v[146:149], v[196:199], v[54:57]
	v_mfma_f32_16x16x32_bf16 v[46:49], v[180:183], v[196:199], v[46:49]
	v_mfma_f32_16x16x32_bf16 v[34:37], v[146:149], v[204:207], v[34:37]
	v_mfma_f32_16x16x32_bf16 v[26:29], v[180:183], v[204:207], v[26:29]
	v_mfma_f32_16x16x32_bf16 v[22:25], v[146:149], v[212:215], v[22:25]
	v_mfma_f32_16x16x32_bf16 v[14:17], v[180:183], v[212:215], v[14:17]
	s_barrier
	s_add_u32 s28, s28, 0x40080
	s_addc_u32 s29, s29, 0
	s_mov_b32 m0, s20
	v_lshl_add_u64 v[130:131], s[28:29], 0, v[0:1]
	global_load_lds_dwordx4 v[130:131], off
	v_lshl_add_u64 v[130:131], s[28:29], 0, v[138:139]
	s_mov_b32 m0, s21
	s_nop 0
	global_load_lds_dwordx4 v[130:131], off
	s_waitcnt vmcnt(6)
	s_barrier
	v_mfma_f32_16x16x32_bf16 v[50:53], v[216:219], v[184:187], v[50:53]
	v_mfma_f32_16x16x32_bf16 v[42:45], v[242:245], v[184:187], v[42:45]
	v_mfma_f32_16x16x32_bf16 v[38:41], v[216:219], v[192:195], v[38:41]
	v_mfma_f32_16x16x32_bf16 v[30:33], v[242:245], v[192:195], v[30:33]
	v_mfma_f32_16x16x32_bf16 v[18:21], v[216:219], v[200:203], v[18:21]
	v_mfma_f32_16x16x32_bf16 v[10:13], v[242:245], v[200:203], v[10:13]
	v_mfma_f32_16x16x32_bf16 v[6:9], v[216:219], v[208:211], v[6:9]
	v_mfma_f32_16x16x32_bf16 v[2:5], v[242:245], v[208:211], v[2:5]
	v_mfma_f32_16x16x32_bf16 v[50:53], v[238:241], v[188:191], v[50:53]
	v_mfma_f32_16x16x32_bf16 v[42:45], v[246:249], v[188:191], v[42:45]
	v_mfma_f32_16x16x32_bf16 v[38:41], v[238:241], v[196:199], v[38:41]
	v_mfma_f32_16x16x32_bf16 v[30:33], v[246:249], v[196:199], v[30:33]
	v_mfma_f32_16x16x32_bf16 v[18:21], v[238:241], v[204:207], v[18:21]
	v_mfma_f32_16x16x32_bf16 v[10:13], v[246:249], v[204:207], v[10:13]
	v_mfma_f32_16x16x32_bf16 v[6:9], v[238:241], v[212:215], v[6:9]
	v_mfma_f32_16x16x32_bf16 v[2:5], v[246:249], v[212:215], v[2:5]
	s_add_i32 s62, s62, 2
	s_add_u32 s80, s80, 0x100
	s_addc_u32 s81, s81, 0
	s_add_u32 s60, s60, 0x100
	s_addc_u32 s61, s61, 0
	s_cmp_gt_u32 s62, 13
	s_barrier
	s_cbranch_scc0 .LBB0_137
	v_mov_b32_e32 v130, 0
	s_and_b64 vcc, exec, s[38:39]
	v_mov_b32_e32 v131, 0
	v_mov_b32_e32 v132, 0
	v_mov_b32_e32 v133, 0
	s_cbranch_vccz .LBB0_140
	v_lshl_add_u32 v130, s26, 8, v150
	v_ashrrev_i32_e32 v131, 31, v130
	v_lshlrev_b64 v[130:131], 5, v[130:131]
	v_lshl_add_u64 v[130:131], v[140:141], 0, v[130:131]
	global_load_dwordx4 v[130:133], v[130:131], off

; #define PG8_STAGE(bufoff, gbase, voff) do { _Pragma("unroll") for (int _i = 0; _i < 2; ++_i) \
;     __builtin_amdgcn_global_load_lds((const unsigned*)((const char*)(gbase) + (voff)[_i]), (PG8_LAS unsigned*)(lds + (bufoff) + ldsw + _i * 8192), 16, 0, 0); } while (0)
; #define PG8_LDA(dst, b, h) do { _Pragma("unroll") for (int m = 0; m < 4; ++m) _Pragma("unroll") for (int k = 0; k < 2; ++k) dst[m][k] = *(const PG8_LAS bf16x8*)(lds + PG8_SA(b, h) + aoff + m * 2048 + k * 1024); } while (0)
; #define PG8_LDB(dst, b, h) do { _Pragma("unroll") for (int n = 0; n < 2; ++n) _Pragma("unroll") for (int k = 0; k < 2; ++k) dst[n][k] = *(const PG8_LAS bf16x8*)(lds + PG8_SB(b, h) + boff + n * 2048 + k * 1024); } while (0)
; #define PG8_MMA(ai, bj, At, Bt) do { __builtin_amdgcn_s_setprio(1); _Pragma("unroll") for (int m = 0; m < 4; ++m) _Pragma("unroll") for (int n = 0; n < 2; ++n) _Pragma("unroll") for (int k = 0; k < 2; ++k) \
;     acc[ai][bj][m][n] = __builtin_amdgcn_mfma_f32_16x16x32_bf16(Bt[n][k], At[m][k], acc[ai][bj][m][n], 0, 0, 0); __builtin_amdgcn_s_setprio(0); } while (0)
; #define PG8_WAIT_L(n) asm volatile("s_waitcnt lgkmcnt(" #n ")" ::: "memory")
; #define PG8_BAR __builtin_amdgcn_s_barrier()
; #define PG8_SCHED __builtin_amdgcn_sched_barrier(0)
; template <class Epi>
; DI void gemm_phase(const bf16_t* __restrict__ gA, const bf16_t* __restrict__ gBt, int M, int N, int K, const Epi& E, char* lds_generic) {
;     ...
;     for (int t = 0; t < nt; t += 2) {
;       const bool last = (t == nt - 2);
;       const char* a1 = cA + (size_t)(t + 1) * kstep;
;       const char* a2 = last ? nA : cA + (size_t)(t + 2) * kstep; const char* b2 = last ? nB : cB + (size_t)(t + 2) * kstep;
;       const char* a3 = a2 + kstep; const char* b3 = b2 + kstep;
;       PG8_LDB(B0, 0, 0); PG8_SCHED; PG8_LDA(At, 0, 0); PG8_STAGE(PG8_SA(1, 1), a1 + hstep, voffA);
;       PG8_WAIT_L(8); PG8_BAR; PG8_WAIT_L(0); PG8_MMA(0, 0, At, B0); PG8_BAR; PG8_SCHED;
;       PG8_LDB(B1, 0, 1); PG8_STAGE(PG8_SB(0, 0), b2, voffB);
;       PG8_BAR; PG8_WAIT_L(0); PG8_MMA(0, 1, At, B1); PG8_BAR;
;       PG8_LDA(At, 0, 1); PG8_STAGE(PG8_SA(0, 0), a2, voffA);
;       PG8_BAR; PG8_WAIT_L(0); PG8_MMA(1, 0, At, B0); PG8_BAR; PG8_SCHED;
.LBB0_159:
	v_or_b32_e32 v130, 0x10000, v155
	v_add_u32_e32 v146, 0x10400, v155
	v_add_u32_e32 v158, 0x10800, v155
	ds_read_b128 v[130:133], v130
	ds_read_b128 v[146:149], v146
	v_add_u32_e32 v163, 0x10c00, v155
	ds_read_b128 v[158:161], v158
	ds_read_b128 v[166:169], v163
	s_add_u32 s23, s80, 0xfffc0080
	s_addc_u32 s24, s81, -1
	s_cmp_eq_u32 s22, 12
	s_cselect_b32 s31, s27, s24
	s_cselect_b32 s30, s58, s23
	s_cselect_b32 s29, s1, s61
	s_cselect_b32 s28, s59, s60
	v_lshl_add_u64 v[202:203], s[80:81], 0, v[142:143]
	s_add_i32 m0, s5, 0xc000
	ds_read_b128 v[170:173], v154
	ds_read_b128 v[174:177], v154 offset:1024
	ds_read_b128 v[178:181], v154 offset:2048
	ds_read_b128 v[182:185], v154 offset:3072
	ds_read_b128 v[186:189], v154 offset:4096
	ds_read_b128 v[190:193], v154 offset:5120
	ds_read_b128 v[194:197], v154 offset:6144
	ds_read_b128 v[198:201], v154 offset:7168
	global_load_lds_dwordx4 v[202:203], off
	v_lshl_add_u64 v[202:203], s[80:81], 0, v[144:145]
	s_add_i32 m0, s5, 0xe000
	s_nop 0
	global_load_lds_dwordx4 v[202:203], off
	s_barrier
	s_waitcnt lgkmcnt(0)
	s_waitcnt lgkmcnt(0)
	v_mfma_f32_16x16x32_bf16 v[126:129], v[130:133], v[170:173], v[126:129]
	v_mfma_f32_16x16x32_bf16 v[122:125], v[158:161], v[170:173], v[122:125]
	v_mfma_f32_16x16x32_bf16 v[118:121], v[130:133], v[178:181], v[118:121]
	v_mfma_f32_16x16x32_bf16 v[110:113], v[158:161], v[178:181], v[110:113]
	v_mfma_f32_16x16x32_bf16 v[98:101], v[130:133], v[186:189], v[98:101]
	v_mfma_f32_16x16x32_bf16 v[90:93], v[158:161], v[186:189], v[90:93]
	v_mfma_f32_16x16x32_bf16 v[86:89], v[130:133], v[194:197], v[86:89]
	v_mfma_f32_16x16x32_bf16 v[78:81], v[158:161], v[194:197], v[78:81]
	v_mfma_f32_16x16x32_bf16 v[126:129], v[146:149], v[174:177], v[126:129]
	v_mfma_f32_16x16x32_bf16 v[122:125], v[166:169], v[174:177], v[122:125]
	v_mfma_f32_16x16x32_bf16 v[118:121], v[146:149], v[182:185], v[118:121]
	v_mfma_f32_16x16x32_bf16 v[110:113], v[166:169], v[182:185], v[110:113]
	v_mfma_f32_16x16x32_bf16 v[98:101], v[146:149], v[190:193], v[98:101]
	v_mfma_f32_16x16x32_bf16 v[90:93], v[166:169], v[190:193], v[90:93]
	v_mfma_f32_16x16x32_bf16 v[86:89], v[146:149], v[198:201], v[86:89]
	v_mfma_f32_16x16x32_bf16 v[78:81], v[166:169], v[198:201], v[78:81]
	s_barrier
	v_or_b32_e32 v163, 0x14000, v155
	s_mov_b32 m0, s6
	v_add_u32_e32 v165, 0x14400, v155
	ds_read_b128 v[202:205], v163
	ds_read_b128 v[206:209], v165
	v_add_u32_e32 v163, 0x14800, v155
	v_lshl_add_u64 v[218:219], s[28:29], 0, v[0:1]
	v_add_u32_e32 v165, 0x14c00, v155
	ds_read_b128 v[210:213], v163
	ds_read_b128 v[214:217], v165
	global_load_lds_dwordx4 v[218:219], off
	v_lshl_add_u64 v[220:221], s[28:29], 0, v[138:139]
	s_mov_b32 m0, s7
	s_nop 0
	global_load_lds_dwordx4 v[220:221], off
	s_barrier
	s_waitcnt lgkmcnt(0)
	s_waitcnt lgkmcnt(0)
	v_mfma_f32_16x16x32_bf16 v[114:117], v[202:205], v[170:173], v[114:117]
	v_mfma_f32_16x16x32_bf16 v[106:109], v[210:213], v[170:173], v[106:109]
	v_mfma_f32_16x16x32_bf16 v[102:105], v[202:205], v[178:181], v[102:105]
	v_mfma_f32_16x16x32_bf16 v[94:97], v[210:213], v[178:181], v[94:97]
	v_mfma_f32_16x16x32_bf16 v[82:85], v[202:205], v[186:189], v[82:85]
	v_mfma_f32_16x16x32_bf16 v[74:77], v[210:213], v[186:189], v[74:77]
	v_mfma_f32_16x16x32_bf16 v[70:73], v[202:205], v[194:197], v[70:73]
	v_mfma_f32_16x16x32_bf16 v[66:69], v[210:213], v[194:197], v[66:69]
	v_mfma_f32_16x16x32_bf16 v[114:117], v[206:209], v[174:177], v[114:117]
	v_mfma_f32_16x16x32_bf16 v[106:109], v[214:217], v[174:177], v[106:109]
	v_mfma_f32_16x16x32_bf16 v[102:105], v[206:209], v[182:185], v[102:105]
	v_mfma_f32_16x16x32_bf16 v[94:97], v[214:217], v[182:185], v[94:97]
	v_mfma_f32_16x16x32_bf16 v[82:85], v[206:209], v[190:193], v[82:85]
	v_mfma_f32_16x16x32_bf16 v[74:77], v[214:217], v[190:193], v[74:77]
	v_mfma_f32_16x16x32_bf16 v[70:73], v[206:209], v[198:201], v[70:73]
	v_mfma_f32_16x16x32_bf16 v[66:69], v[214:217], v[198:201], v[66:69]
	s_mov_b32 m0, s5
	v_lshl_add_u64 v[238:239], s[30:31], 0, v[134:135]
	s_barrier
	ds_read_b128 v[170:173], v154 offset:16384
	ds_read_b128 v[174:177], v154 offset:17408
	ds_read_b128 v[178:181], v154 offset:18432
	ds_read_b128 v[182:185], v154 offset:19456
	ds_read_b128 v[186:189], v154 offset:20480
	ds_read_b128 v[190:193], v154 offset:21504
	ds_read_b128 v[194:197], v154 offset:22528
	ds_read_b128 v[198:201], v154 offset:23552
	global_load_lds_dwordx4 v[238:239], off
	v_lshl_add_u64 v[240:241], s[30:31], 0, v[136:137]
	s_mov_b32 m0, s8
	s_nop 0
	global_load_lds_dwordx4 v[240:241], off
	s_barrier
	s_waitcnt lgkmcnt(0)
	s_waitcnt lgkmcnt(0)
	v_mfma_f32_16x16x32_bf16 v[62:65], v[130:133], v[170:173], v[62:65]
	v_mfma_f32_16x16x32_bf16 v[58:61], v[158:161], v[170:173], v[58:61]
	v_mfma_f32_16x16x32_bf16 v[54:57], v[130:133], v[178:181], v[54:57]
	v_mfma_f32_16x16x32_bf16 v[46:49], v[158:161], v[178:181], v[46:49]
	v_mfma_f32_16x16x32_bf16 v[34:37], v[130:133], v[186:189], v[34:37]
	v_mfma_f32_16x16x32_bf16 v[26:29], v[158:161], v[186:189], v[26:29]
	v_mfma_f32_16x16x32_bf16 v[22:25], v[130:133], v[194:197], v[22:25]
	v_mfma_f32_16x16x32_bf16 v[14:17], v[158:161], v[194:197], v[14:17]
	v_mfma_f32_16x16x32_bf16 v[62:65], v[146:149], v[174:177], v[62:65]
	v_mfma_f32_16x16x32_bf16 v[58:61], v[166:169], v[174:177], v[58:61]
	v_mfma_f32_16x16x32_bf16 v[54:57], v[146:149], v[182:185], v[54:57]
	v_mfma_f32_16x16x32_bf16 v[46:49], v[166:169], v[182:185], v[46:49]
	v_mfma_f32_16x16x32_bf16 v[34:37], v[146:149], v[190:193], v[34:37]
	v_mfma_f32_16x16x32_bf16 v[26:29], v[166:169], v[190:193], v[26:29]
	v_mfma_f32_16x16x32_bf16 v[22:25], v[146:149], v[198:201], v[22:25]
	v_mfma_f32_16x16x32_bf16 v[14:17], v[166:169], v[198:201], v[14:17]
	s_barrier
; #define PG8_STAGE(bufoff, gbase, voff) do { _Pragma("unroll") for (int _i = 0; _i < 2; ++_i) \
;     __builtin_amdgcn_global_load_lds((const unsigned*)((const char*)(gbase) + (voff)[_i]), (PG8_LAS unsigned*)(lds + (bufoff) + ldsw + _i * 8192), 16, 0, 0); } while (0)
; #define PG8_LDA(dst, b, h) do { _Pragma("unroll") for (int m = 0; m < 4; ++m) _Pragma("unroll") for (int k = 0; k < 2; ++k) dst[m][k] = *(const PG8_LAS bf16x8*)(lds + PG8_SA(b, h) + aoff + m * 2048 + k * 1024); } while (0)
; #define PG8_LDB(dst, b, h) do { _Pragma("unroll") for (int n = 0; n < 2; ++n) _Pragma("unroll") for (int k = 0; k < 2; ++k) dst[n][k] = *(const PG8_LAS bf16x8*)(lds + PG8_SB(b, h) + boff + n * 2048 + k * 1024); } while (0)
; #define PG8_MMA(ai, bj, At, Bt) do { __builtin_amdgcn_s_setprio(1); _Pragma("unroll") for (int m = 0; m < 4; ++m) _Pragma("unroll") for (int n = 0; n < 2; ++n) _Pragma("unroll") for (int k = 0; k < 2; ++k) \
;     acc[ai][bj][m][n] = __builtin_amdgcn_mfma_f32_16x16x32_bf16(Bt[n][k], At[m][k], acc[ai][bj][m][n], 0, 0, 0); __builtin_amdgcn_s_setprio(0); } while (0)
; #define PG8_WAIT_V(n) asm volatile("s_waitcnt vmcnt(" #n ")" ::: "memory")
; #define PG8_WAIT_L(n) asm volatile("s_waitcnt lgkmcnt(" #n ")" ::: "memory")
; #define PG8_BAR __builtin_amdgcn_s_barrier()
; #define PG8_SCHED __builtin_amdgcn_sched_barrier(0)
; template <class Epi>
; DI void gemm_phase(const bf16_t* __restrict__ gA, const bf16_t* __restrict__ gBt, int M, int N, int K, const Epi& E, char* lds_generic) {
;     ...
;       PG8_STAGE(PG8_SB(0, 1), b2 + hstep, voffB);
;       PG8_WAIT_V(6); PG8_BAR; PG8_MMA(1, 1, At, B1); PG8_BAR;
;       PG8_LDB(B0, 1, 0); PG8_SCHED; PG8_LDA(At, 1, 0); PG8_STAGE(PG8_SA(0, 1), a2 + hstep, voffA);
;       PG8_WAIT_L(8); PG8_BAR; PG8_WAIT_L(0); PG8_MMA(0, 0, At, B0); PG8_BAR; PG8_SCHED;
;       PG8_LDB(B1, 1, 1); PG8_STAGE(PG8_SB(1, 0), b3, voffB);
;       PG8_BAR; PG8_WAIT_L(0); PG8_MMA(0, 1, At, B1); PG8_BAR;
	s_add_u32 s82, s28, 0x40000
	s_addc_u32 s83, s29, 0
	s_mov_b32 m0, s9
	v_lshl_add_u64 v[130:131], s[82:83], 0, v[0:1]
	global_load_lds_dwordx4 v[130:131], off
	v_lshl_add_u64 v[130:131], s[82:83], 0, v[138:139]
	s_mov_b32 m0, s12
	s_nop 0
	global_load_lds_dwordx4 v[130:131], off
	s_waitcnt vmcnt(6)
	s_barrier
	v_mfma_f32_16x16x32_bf16 v[50:53], v[202:205], v[170:173], v[50:53]
	v_mfma_f32_16x16x32_bf16 v[42:45], v[210:213], v[170:173], v[42:45]
	v_mfma_f32_16x16x32_bf16 v[38:41], v[202:205], v[178:181], v[38:41]
	v_mfma_f32_16x16x32_bf16 v[30:33], v[210:213], v[178:181], v[30:33]
	v_mfma_f32_16x16x32_bf16 v[18:21], v[202:205], v[186:189], v[18:21]
	v_mfma_f32_16x16x32_bf16 v[10:13], v[210:213], v[186:189], v[10:13]
	v_mfma_f32_16x16x32_bf16 v[6:9], v[202:205], v[194:197], v[6:9]
	v_mfma_f32_16x16x32_bf16 v[2:5], v[210:213], v[194:197], v[2:5]
	v_mfma_f32_16x16x32_bf16 v[50:53], v[206:209], v[174:177], v[50:53]
	v_mfma_f32_16x16x32_bf16 v[42:45], v[214:217], v[174:177], v[42:45]
	v_mfma_f32_16x16x32_bf16 v[38:41], v[206:209], v[182:185], v[38:41]
	v_mfma_f32_16x16x32_bf16 v[30:33], v[214:217], v[182:185], v[30:33]
	v_mfma_f32_16x16x32_bf16 v[18:21], v[206:209], v[190:193], v[18:21]
	v_mfma_f32_16x16x32_bf16 v[10:13], v[214:217], v[190:193], v[10:13]
	v_mfma_f32_16x16x32_bf16 v[6:9], v[206:209], v[198:201], v[6:9]
	v_mfma_f32_16x16x32_bf16 v[2:5], v[214:217], v[198:201], v[2:5]
	v_or_b32_e32 v130, 0x18000, v155
	v_add_u32_e32 v146, 0x18400, v155
	v_add_u32_e32 v158, 0x18800, v155
	s_barrier
	ds_read_b128 v[130:133], v130
	ds_read_b128 v[146:149], v146
	v_add_u32_e32 v163, 0x18c00, v155
	ds_read_b128 v[158:161], v158
	ds_read_b128 v[166:169], v163
	s_add_u32 s30, s30, 0x40000
	s_addc_u32 s31, s31, 0
	s_mov_b32 m0, s13
	v_lshl_add_u64 v[202:203], s[30:31], 0, v[134:135]
	ds_read_b128 v[170:173], v154 offset:32768
	ds_read_b128 v[174:177], v154 offset:33792
	ds_read_b128 v[178:181], v154 offset:34816
	ds_read_b128 v[182:185], v154 offset:35840
	ds_read_b128 v[186:189], v154 offset:36864
	ds_read_b128 v[190:193], v154 offset:37888
	ds_read_b128 v[194:197], v154 offset:38912
	ds_read_b128 v[198:201], v154 offset:39936
	global_load_lds_dwordx4 v[202:203], off
	v_lshl_add_u64 v[202:203], s[30:31], 0, v[136:137]
	s_mov_b32 m0, s14
	s_nop 0
	global_load_lds_dwordx4 v[202:203], off
	s_barrier
	s_waitcnt lgkmcnt(0)
	s_waitcnt lgkmcnt(0)
	v_mfma_f32_16x16x32_bf16 v[126:129], v[130:133], v[170:173], v[126:129]
	v_mfma_f32_16x16x32_bf16 v[122:125], v[158:161], v[170:173], v[122:125]
	v_mfma_f32_16x16x32_bf16 v[118:121], v[130:133], v[178:181], v[118:121]
	v_mfma_f32_16x16x32_bf16 v[110:113], v[158:161], v[178:181], v[110:113]
	v_mfma_f32_16x16x32_bf16 v[98:101], v[130:133], v[186:189], v[98:101]
	v_mfma_f32_16x16x32_bf16 v[90:93], v[158:161], v[186:189], v[90:93]
	v_mfma_f32_16x16x32_bf16 v[86:89], v[130:133], v[194:197], v[86:89]
	v_mfma_f32_16x16x32_bf16 v[78:81], v[158:161], v[194:197], v[78:81]
	v_mfma_f32_16x16x32_bf16 v[126:129], v[146:149], v[174:177], v[126:129]
	v_mfma_f32_16x16x32_bf16 v[122:125], v[166:169], v[174:177], v[122:125]
	v_mfma_f32_16x16x32_bf16 v[118:121], v[146:149], v[182:185], v[118:121]
	v_mfma_f32_16x16x32_bf16 v[110:113], v[166:169], v[182:185], v[110:113]
	v_mfma_f32_16x16x32_bf16 v[98:101], v[146:149], v[190:193], v[98:101]
	v_mfma_f32_16x16x32_bf16 v[90:93], v[166:169], v[190:193], v[90:93]
	v_mfma_f32_16x16x32_bf16 v[86:89], v[146:149], v[198:201], v[86:89]
	v_mfma_f32_16x16x32_bf16 v[78:81], v[166:169], v[198:201], v[78:81]
	s_barrier
	v_or_b32_e32 v163, 0x1c000, v155
	s_mov_b32 m0, s15
	v_add_u32_e32 v165, 0x1c400, v155
	ds_read_b128 v[202:205], v163
	ds_read_b128 v[206:209], v165
	v_add_u32_e32 v163, 0x1c800, v155
	v_lshl_add_u64 v[218:219], v[218:219], 0, s[10:11]
	v_add_u32_e32 v165, 0x1cc00, v155
	ds_read_b128 v[210:213], v163
	ds_read_b128 v[214:217], v165
	global_load_lds_dwordx4 v[218:219], off
	v_lshl_add_u64 v[218:219], v[220:221], 0, s[10:11]
	s_mov_b32 m0, s16
	s_nop 0
	global_load_lds_dwordx4 v[218:219], off
	s_barrier
; #define PG8_STAGE(bufoff, gbase, voff) do { _Pragma("unroll") for (int _i = 0; _i < 2; ++_i) \
;     __builtin_amdgcn_global_load_lds((const unsigned*)((const char*)(gbase) + (voff)[_i]), (PG8_LAS unsigned*)(lds + (bufoff) + ldsw + _i * 8192), 16, 0, 0); } while (0)
; #define PG8_LDA(dst, b, h) do { _Pragma("unroll") for (int m = 0; m < 4; ++m) _Pragma("unroll") for (int k = 0; k < 2; ++k) dst[m][k] = *(const PG8_LAS bf16x8*)(lds + PG8_SA(b, h) + aoff + m * 2048 + k * 1024); } while (0)
; #define PG8_MMA(ai, bj, At, Bt) do { __builtin_amdgcn_s_setprio(1); _Pragma("unroll") for (int m = 0; m < 4; ++m) _Pragma("unroll") for (int n = 0; n < 2; ++n) _Pragma("unroll") for (int k = 0; k < 2; ++k) \
;     acc[ai][bj][m][n] = __builtin_amdgcn_mfma_f32_16x16x32_bf16(Bt[n][k], At[m][k], acc[ai][bj][m][n], 0, 0, 0); __builtin_amdgcn_s_setprio(0); } while (0)
; #define PG8_WAIT_V(n) asm volatile("s_waitcnt vmcnt(" #n ")" ::: "memory")
; #define PG8_WAIT_L(n) asm volatile("s_waitcnt lgkmcnt(" #n ")" ::: "memory")
; #define PG8_BAR __builtin_amdgcn_s_barrier()
; #define PG8_SCHED __builtin_amdgcn_sched_barrier(0)
; #define PG8_RTAB_LOAD(var, unit) do { if constexpr (Epi::NEEDS_R) { var = *(const uint4*)(E.ssq + (size_t)((unit).pm * BM + (tid >> 1)) * 16 + (tid & 1) * 8); } } while (0)
; template <class Epi>
; DI void gemm_phase(const bf16_t* __restrict__ gA, const bf16_t* __restrict__ gBt, int M, int N, int K, const Epi& E, char* lds_generic) {
;     ...
;       PG8_BAR; PG8_WAIT_L(0); PG8_MMA(0, 1, At, B1); PG8_BAR;
;       PG8_LDA(At, 1, 1); PG8_STAGE(PG8_SA(1, 0), a3, voffA);
;       PG8_BAR; PG8_WAIT_L(0); PG8_MMA(1, 0, At, B0); PG8_BAR; PG8_SCHED;
;       PG8_STAGE(PG8_SB(1, 1), b3 + hstep, voffB);
;       PG8_WAIT_V(6); PG8_BAR; PG8_MMA(1, 1, At, B1); PG8_BAR;
;     }
;     uint4 rtn_ = {0u, 0u, 0u, 0u};
;     if (has_next) PG8_RTAB_LOAD(rtn_, nxt);
	s_waitcnt lgkmcnt(0)
	s_waitcnt lgkmcnt(0)
	v_mfma_f32_16x16x32_bf16 v[114:117], v[202:205], v[170:173], v[114:117]
	v_mfma_f32_16x16x32_bf16 v[106:109], v[210:213], v[170:173], v[106:109]
	v_mfma_f32_16x16x32_bf16 v[102:105], v[202:205], v[178:181], v[102:105]
	v_mfma_f32_16x16x32_bf16 v[94:97], v[210:213], v[178:181], v[94:97]
	v_mfma_f32_16x16x32_bf16 v[82:85], v[202:205], v[186:189], v[82:85]
	v_mfma_f32_16x16x32_bf16 v[74:77], v[210:213], v[186:189], v[74:77]
	v_mfma_f32_16x16x32_bf16 v[70:73], v[202:205], v[194:197], v[70:73]
	v_mfma_f32_16x16x32_bf16 v[66:69], v[210:213], v[194:197], v[66:69]
	v_mfma_f32_16x16x32_bf16 v[114:117], v[206:209], v[174:177], v[114:117]
	v_mfma_f32_16x16x32_bf16 v[106:109], v[214:217], v[174:177], v[106:109]
	v_mfma_f32_16x16x32_bf16 v[102:105], v[206:209], v[182:185], v[102:105]
	v_mfma_f32_16x16x32_bf16 v[94:97], v[214:217], v[182:185], v[94:97]
	v_mfma_f32_16x16x32_bf16 v[82:85], v[206:209], v[190:193], v[82:85]
	v_mfma_f32_16x16x32_bf16 v[74:77], v[214:217], v[190:193], v[74:77]
	v_mfma_f32_16x16x32_bf16 v[70:73], v[206:209], v[198:201], v[70:73]
	v_mfma_f32_16x16x32_bf16 v[66:69], v[214:217], v[198:201], v[66:69]
	s_mov_b32 m0, s18
	v_lshl_add_u64 v[218:219], v[238:239], 0, s[10:11]
	s_barrier
	ds_read_b128 v[170:173], v154 offset:49152
	ds_read_b128 v[174:177], v154 offset:50176
	ds_read_b128 v[178:181], v154 offset:51200
	ds_read_b128 v[182:185], v154 offset:52224
	ds_read_b128 v[186:189], v154 offset:53248
	ds_read_b128 v[190:193], v154 offset:54272
	ds_read_b128 v[194:197], v154 offset:55296
	ds_read_b128 v[198:201], v154 offset:56320
	global_load_lds_dwordx4 v[218:219], off
	v_lshl_add_u64 v[218:219], v[240:241], 0, s[10:11]
	s_mov_b32 m0, s19
	s_nop 0
	global_load_lds_dwordx4 v[218:219], off
	s_barrier
	s_waitcnt lgkmcnt(0)
	s_waitcnt lgkmcnt(0)
	v_mfma_f32_16x16x32_bf16 v[62:65], v[130:133], v[170:173], v[62:65]
	v_mfma_f32_16x16x32_bf16 v[58:61], v[158:161], v[170:173], v[58:61]
	v_mfma_f32_16x16x32_bf16 v[54:57], v[130:133], v[178:181], v[54:57]
	v_mfma_f32_16x16x32_bf16 v[46:49], v[158:161], v[178:181], v[46:49]
	v_mfma_f32_16x16x32_bf16 v[34:37], v[130:133], v[186:189], v[34:37]
	v_mfma_f32_16x16x32_bf16 v[26:29], v[158:161], v[186:189], v[26:29]
	v_mfma_f32_16x16x32_bf16 v[22:25], v[130:133], v[194:197], v[22:25]
	v_mfma_f32_16x16x32_bf16 v[14:17], v[158:161], v[194:197], v[14:17]
	v_mfma_f32_16x16x32_bf16 v[62:65], v[146:149], v[174:177], v[62:65]
	v_mfma_f32_16x16x32_bf16 v[58:61], v[166:169], v[174:177], v[58:61]
	v_mfma_f32_16x16x32_bf16 v[54:57], v[146:149], v[182:185], v[54:57]
	v_mfma_f32_16x16x32_bf16 v[46:49], v[166:169], v[182:185], v[46:49]
	v_mfma_f32_16x16x32_bf16 v[34:37], v[146:149], v[190:193], v[34:37]
	v_mfma_f32_16x16x32_bf16 v[26:29], v[166:169], v[190:193], v[26:29]
	v_mfma_f32_16x16x32_bf16 v[22:25], v[146:149], v[198:201], v[22:25]
	v_mfma_f32_16x16x32_bf16 v[14:17], v[166:169], v[198:201], v[14:17]
	s_barrier
	s_add_u32 s28, s28, 0x40080
	s_addc_u32 s29, s29, 0
	s_mov_b32 m0, s20
	v_lshl_add_u64 v[130:131], s[28:29], 0, v[0:1]
	global_load_lds_dwordx4 v[130:131], off
	v_lshl_add_u64 v[130:131], s[28:29], 0, v[138:139]
	s_mov_b32 m0, s21
	s_nop 0
	global_load_lds_dwordx4 v[130:131], off
	s_waitcnt vmcnt(6)
	s_barrier
	v_mfma_f32_16x16x32_bf16 v[50:53], v[202:205], v[170:173], v[50:53]
	v_mfma_f32_16x16x32_bf16 v[42:45], v[210:213], v[170:173], v[42:45]
	v_mfma_f32_16x16x32_bf16 v[38:41], v[202:205], v[178:181], v[38:41]
	v_mfma_f32_16x16x32_bf16 v[30:33], v[210:213], v[178:181], v[30:33]
	v_mfma_f32_16x16x32_bf16 v[18:21], v[202:205], v[186:189], v[18:21]
	v_mfma_f32_16x16x32_bf16 v[10:13], v[210:213], v[186:189], v[10:13]
	v_mfma_f32_16x16x32_bf16 v[6:9], v[202:205], v[194:197], v[6:9]
	v_mfma_f32_16x16x32_bf16 v[2:5], v[210:213], v[194:197], v[2:5]
	v_mfma_f32_16x16x32_bf16 v[50:53], v[206:209], v[174:177], v[50:53]
	v_mfma_f32_16x16x32_bf16 v[42:45], v[214:217], v[174:177], v[42:45]
	v_mfma_f32_16x16x32_bf16 v[38:41], v[206:209], v[182:185], v[38:41]
	v_mfma_f32_16x16x32_bf16 v[30:33], v[214:217], v[182:185], v[30:33]
	v_mfma_f32_16x16x32_bf16 v[18:21], v[206:209], v[190:193], v[18:21]
	v_mfma_f32_16x16x32_bf16 v[10:13], v[214:217], v[190:193], v[10:13]
	v_mfma_f32_16x16x32_bf16 v[6:9], v[206:209], v[198:201], v[6:9]
	v_mfma_f32_16x16x32_bf16 v[2:5], v[214:217], v[198:201], v[2:5]
	s_add_i32 s22, s22, 2
	s_add_u32 s80, s80, 0x100
	s_addc_u32 s81, s81, 0
	s_add_u32 s60, s60, 0x100
	s_addc_u32 s61, s61, 0
	s_cmp_gt_u32 s22, 13
	s_barrier
	s_cbranch_scc0 .LBB0_159
	v_mov_b32_e32 v130, 0
	s_and_b64 vcc, exec, s[38:39]
	v_mov_b32_e32 v131, 0
	v_mov_b32_e32 v132, 0
	v_mov_b32_e32 v133, 0
	s_cbranch_vccz .LBB0_162
	v_lshl_add_u32 v130, s26, 8, v150
	v_ashrrev_i32_e32 v131, 31, v130
	v_lshlrev_b64 v[130:131], 5, v[130:131]
	v_lshl_add_u64 v[130:131], v[140:141], 0, v[130:131]
	global_load_dwordx4 v[130:133], v[130:131], off

; #define PG8_STAGE(bufoff, gbase, voff) do { _Pragma("unroll") for (int _i = 0; _i < 2; ++_i) \
;     __builtin_amdgcn_global_load_lds((const unsigned*)((const char*)(gbase) + (voff)[_i]), (PG8_LAS unsigned*)(lds + (bufoff) + ldsw + _i * 8192), 16, 0, 0); } while (0)
; #define PG8_LDA(dst, b, h) do { _Pragma("unroll") for (int m = 0; m < 4; ++m) _Pragma("unroll") for (int k = 0; k < 2; ++k) dst[m][k] = *(const PG8_LAS bf16x8*)(lds + PG8_SA(b, h) + aoff + m * 2048 + k * 1024); } while (0)
; #define PG8_LDB(dst, b, h) do { _Pragma("unroll") for (int n = 0; n < 2; ++n) _Pragma("unroll") for (int k = 0; k < 2; ++k) dst[n][k] = *(const PG8_LAS bf16x8*)(lds + PG8_SB(b, h) + boff + n * 2048 + k * 1024); } while (0)
; #define PG8_MMA(ai, bj, At, Bt) do { __builtin_amdgcn_s_setprio(1); _Pragma("unroll") for (int m = 0; m < 4; ++m) _Pragma("unroll") for (int n = 0; n < 2; ++n) _Pragma("unroll") for (int k = 0; k < 2; ++k) \
;     acc[ai][bj][m][n] = __builtin_amdgcn_mfma_f32_16x16x32_bf16(Bt[n][k], At[m][k], acc[ai][bj][m][n], 0, 0, 0); __builtin_amdgcn_s_setprio(0); } while (0)
; #define PG8_WAIT_L(n) asm volatile("s_waitcnt lgkmcnt(" #n ")" ::: "memory")
; #define PG8_BAR __builtin_amdgcn_s_barrier()
; #define PG8_SCHED __builtin_amdgcn_sched_barrier(0)
; template <class Epi>
; DI void gemm_phase(const bf16_t* __restrict__ gA, const bf16_t* __restrict__ gBt, int M, int N, int K, const Epi& E, char* lds_generic) {
;     ...
;     for (int t = 0; t < nt; t += 2) {
;       const bool last = (t == nt - 2);
;       const char* a1 = cA + (size_t)(t + 1) * kstep;
;       const char* a2 = last ? nA : cA + (size_t)(t + 2) * kstep; const char* b2 = last ? nB : cB + (size_t)(t + 2) * kstep;
;       const char* a3 = a2 + kstep; const char* b3 = b2 + kstep;
;       PG8_LDB(B0, 0, 0); PG8_SCHED; PG8_LDA(At, 0, 0); PG8_STAGE(PG8_SA(1, 1), a1 + hstep, voffA);
;       PG8_WAIT_L(8); PG8_BAR; PG8_WAIT_L(0); PG8_MMA(0, 0, At, B0); PG8_BAR; PG8_SCHED;
;       PG8_LDB(B1, 0, 1); PG8_STAGE(PG8_SB(0, 0), b2, voffB);
;       PG8_BAR; PG8_WAIT_L(0); PG8_MMA(0, 1, At, B1); PG8_BAR;
;       PG8_LDA(At, 0, 1); PG8_STAGE(PG8_SA(0, 0), a2, voffA);
;       PG8_BAR; PG8_WAIT_L(0); PG8_MMA(1, 0, At, B0); PG8_BAR; PG8_SCHED;
.LBB0_511:
	v_or_b32_e32 v140, 0x10000, v146
	v_add_u32_e32 v148, 0x10400, v146
	v_add_u32_e32 v152, 0x10800, v146
	v_add_u32_e32 v156, 0x10c00, v146
	ds_read_b128 v[140:143], v140
	ds_read_b128 v[148:151], v148
	ds_read_b128 v[152:155], v152
	ds_read_b128 v[156:159], v156
	s_add_u32 s0, s28, 0xfffc0080
	s_addc_u32 s1, s29, -1
	s_cmp_eq_u32 s60, 12
	s_cselect_b32 s31, s22, s1
	s_cselect_b32 s30, s23, s0
	s_cselect_b32 s1, s27, s59
	s_cselect_b32 s0, s39, s58
	v_lshl_add_u64 v[160:161], s[28:29], 0, v[136:137]
	s_add_i32 m0, s6, 0xc000
	ds_read_b128 v[166:169], v145
	ds_read_b128 v[170:173], v145 offset:1024
	ds_read_b128 v[174:177], v145 offset:2048
	ds_read_b128 v[178:181], v145 offset:3072
	ds_read_b128 v[182:185], v145 offset:4096
	ds_read_b128 v[186:189], v145 offset:5120
	ds_read_b128 v[190:193], v145 offset:6144
	ds_read_b128 v[194:197], v145 offset:7168
	global_load_lds_dwordx4 v[160:161], off
	v_lshl_add_u64 v[160:161], s[28:29], 0, v[138:139]
	s_add_i32 m0, s6, 0xe000
	s_nop 0
	global_load_lds_dwordx4 v[160:161], off
	s_barrier
	s_waitcnt lgkmcnt(0)
	s_waitcnt lgkmcnt(0)
	v_mfma_f32_16x16x32_bf16 v[118:121], v[140:143], v[166:169], v[118:121]
	v_mfma_f32_16x16x32_bf16 v[110:113], v[152:155], v[166:169], v[110:113]
	v_mfma_f32_16x16x32_bf16 v[90:93], v[140:143], v[174:177], v[90:93]
	v_mfma_f32_16x16x32_bf16 v[82:85], v[152:155], v[174:177], v[82:85]
	v_mfma_f32_16x16x32_bf16 v[62:65], v[140:143], v[182:185], v[62:65]
	v_mfma_f32_16x16x32_bf16 v[50:53], v[152:155], v[182:185], v[50:53]
	v_mfma_f32_16x16x32_bf16 v[42:45], v[140:143], v[190:193], v[42:45]
	v_mfma_f32_16x16x32_bf16 v[22:25], v[152:155], v[190:193], v[22:25]
	v_mfma_f32_16x16x32_bf16 v[118:121], v[148:151], v[170:173], v[118:121]
	v_mfma_f32_16x16x32_bf16 v[110:113], v[156:159], v[170:173], v[110:113]
	v_mfma_f32_16x16x32_bf16 v[90:93], v[148:151], v[178:181], v[90:93]
	v_mfma_f32_16x16x32_bf16 v[82:85], v[156:159], v[178:181], v[82:85]
	v_mfma_f32_16x16x32_bf16 v[62:65], v[148:151], v[186:189], v[62:65]
	v_mfma_f32_16x16x32_bf16 v[50:53], v[156:159], v[186:189], v[50:53]
	v_mfma_f32_16x16x32_bf16 v[42:45], v[148:151], v[194:197], v[42:45]
	v_mfma_f32_16x16x32_bf16 v[22:25], v[156:159], v[194:197], v[22:25]
	s_barrier
	v_or_b32_e32 v160, 0x14000, v146
	v_add_u32_e32 v161, 0x14400, v146
	ds_read_b128 v[198:201], v160
	ds_read_b128 v[202:205], v161
	v_add_u32_e32 v160, 0x14800, v146
	v_add_u32_e32 v161, 0x14c00, v146
	s_mov_b32 m0, s7
	ds_read_b128 v[206:209], v160
	ds_read_b128 v[210:213], v161
	v_lshl_add_u64 v[160:161], s[0:1], 0, v[0:1]
	global_load_lds_dwordx4 v[160:161], off
	v_lshl_add_u64 v[214:215], s[0:1], 0, v[130:131]
	s_mov_b32 m0, s12
	s_nop 0
	global_load_lds_dwordx4 v[214:215], off
	s_barrier
	s_waitcnt lgkmcnt(0)
	s_waitcnt lgkmcnt(0)
	v_mfma_f32_16x16x32_bf16 v[122:125], v[198:201], v[166:169], v[122:125]
	v_mfma_f32_16x16x32_bf16 v[126:129], v[206:209], v[166:169], v[126:129]
	v_mfma_f32_16x16x32_bf16 v[102:105], v[198:201], v[174:177], v[102:105]
	v_mfma_f32_16x16x32_bf16 v[114:117], v[206:209], v[174:177], v[114:117]
	v_mfma_f32_16x16x32_bf16 v[86:89], v[198:201], v[182:185], v[86:89]
	v_mfma_f32_16x16x32_bf16 v[98:101], v[206:209], v[182:185], v[98:101]
	v_mfma_f32_16x16x32_bf16 v[58:61], v[198:201], v[190:193], v[58:61]
	v_mfma_f32_16x16x32_bf16 v[74:77], v[206:209], v[190:193], v[74:77]
	v_mfma_f32_16x16x32_bf16 v[122:125], v[202:205], v[170:173], v[122:125]
	v_mfma_f32_16x16x32_bf16 v[126:129], v[210:213], v[170:173], v[126:129]
	v_mfma_f32_16x16x32_bf16 v[102:105], v[202:205], v[178:181], v[102:105]
	v_mfma_f32_16x16x32_bf16 v[114:117], v[210:213], v[178:181], v[114:117]
	v_mfma_f32_16x16x32_bf16 v[86:89], v[202:205], v[186:189], v[86:89]
	v_mfma_f32_16x16x32_bf16 v[98:101], v[210:213], v[186:189], v[98:101]
	v_mfma_f32_16x16x32_bf16 v[58:61], v[202:205], v[194:197], v[58:61]
	v_mfma_f32_16x16x32_bf16 v[74:77], v[210:213], v[194:197], v[74:77]
	s_mov_b32 m0, s6
	v_lshl_add_u64 v[216:217], s[30:31], 0, v[134:135]
	s_barrier
	ds_read_b128 v[166:169], v145 offset:16384
	ds_read_b128 v[170:173], v145 offset:17408
	ds_read_b128 v[174:177], v145 offset:18432
	ds_read_b128 v[178:181], v145 offset:19456
	ds_read_b128 v[182:185], v145 offset:20480
	ds_read_b128 v[186:189], v145 offset:21504
	ds_read_b128 v[190:193], v145 offset:22528
	ds_read_b128 v[194:197], v145 offset:23552
	global_load_lds_dwordx4 v[216:217], off
	v_lshl_add_u64 v[218:219], s[30:31], 0, v[132:133]
	s_mov_b32 m0, s13
	s_nop 0
	global_load_lds_dwordx4 v[218:219], off
	s_barrier
	s_waitcnt lgkmcnt(0)
	s_waitcnt lgkmcnt(0)
	v_mfma_f32_16x16x32_bf16 v[38:41], v[140:143], v[166:169], v[38:41]
	v_mfma_f32_16x16x32_bf16 v[18:21], v[152:155], v[166:169], v[18:21]
	v_mfma_f32_16x16x32_bf16 v[10:13], v[140:143], v[174:177], v[10:13]
	v_mfma_f32_16x16x32_bf16 v[2:5], v[152:155], v[174:177], v[2:5]
	v_mfma_f32_16x16x32_bf16 v[46:49], v[140:143], v[182:185], v[46:49]
	v_mfma_f32_16x16x32_bf16 v[30:33], v[152:155], v[182:185], v[30:33]
	v_mfma_f32_16x16x32_bf16 v[14:17], v[140:143], v[190:193], v[14:17]
	v_mfma_f32_16x16x32_bf16 v[6:9], v[152:155], v[190:193], v[6:9]
	v_mfma_f32_16x16x32_bf16 v[38:41], v[148:151], v[170:173], v[38:41]
	v_mfma_f32_16x16x32_bf16 v[18:21], v[156:159], v[170:173], v[18:21]
	v_mfma_f32_16x16x32_bf16 v[10:13], v[148:151], v[178:181], v[10:13]
	v_mfma_f32_16x16x32_bf16 v[2:5], v[156:159], v[178:181], v[2:5]
	v_mfma_f32_16x16x32_bf16 v[46:49], v[148:151], v[186:189], v[46:49]
	v_mfma_f32_16x16x32_bf16 v[30:33], v[156:159], v[186:189], v[30:33]
	v_mfma_f32_16x16x32_bf16 v[14:17], v[148:151], v[194:197], v[14:17]
	v_mfma_f32_16x16x32_bf16 v[6:9], v[156:159], v[194:197], v[6:9]
	s_barrier
; #define PG8_STAGE(bufoff, gbase, voff) do { _Pragma("unroll") for (int _i = 0; _i < 2; ++_i) \
;     __builtin_amdgcn_global_load_lds((const unsigned*)((const char*)(gbase) + (voff)[_i]), (PG8_LAS unsigned*)(lds + (bufoff) + ldsw + _i * 8192), 16, 0, 0); } while (0)
; #define PG8_LDA(dst, b, h) do { _Pragma("unroll") for (int m = 0; m < 4; ++m) _Pragma("unroll") for (int k = 0; k < 2; ++k) dst[m][k] = *(const PG8_LAS bf16x8*)(lds + PG8_SA(b, h) + aoff + m * 2048 + k * 1024); } while (0)
; #define PG8_LDB(dst, b, h) do { _Pragma("unroll") for (int n = 0; n < 2; ++n) _Pragma("unroll") for (int k = 0; k < 2; ++k) dst[n][k] = *(const PG8_LAS bf16x8*)(lds + PG8_SB(b, h) + boff + n * 2048 + k * 1024); } while (0)
; #define PG8_MMA(ai, bj, At, Bt) do { __builtin_amdgcn_s_setprio(1); _Pragma("unroll") for (int m = 0; m < 4; ++m) _Pragma("unroll") for (int n = 0; n < 2; ++n) _Pragma("unroll") for (int k = 0; k < 2; ++k) \
;     acc[ai][bj][m][n] = __builtin_amdgcn_mfma_f32_16x16x32_bf16(Bt[n][k], At[m][k], acc[ai][bj][m][n], 0, 0, 0); __builtin_amdgcn_s_setprio(0); } while (0)
; #define PG8_WAIT_V(n) asm volatile("s_waitcnt vmcnt(" #n ")" ::: "memory")
; #define PG8_WAIT_L(n) asm volatile("s_waitcnt lgkmcnt(" #n ")" ::: "memory")
; #define PG8_BAR __builtin_amdgcn_s_barrier()
; #define PG8_SCHED __builtin_amdgcn_sched_barrier(0)
; template <class Epi>
; DI void gemm_phase(const bf16_t* __restrict__ gA, const bf16_t* __restrict__ gBt, int M, int N, int K, const Epi& E, char* lds_generic) {
;     ...
;       PG8_STAGE(PG8_SB(0, 1), b2 + hstep, voffB);
;       PG8_WAIT_V(6); PG8_BAR; PG8_MMA(1, 1, At, B1); PG8_BAR;
;       PG8_LDB(B0, 1, 0); PG8_SCHED; PG8_LDA(At, 1, 0); PG8_STAGE(PG8_SA(0, 1), a2 + hstep, voffA);
;       PG8_WAIT_L(8); PG8_BAR; PG8_WAIT_L(0); PG8_MMA(0, 0, At, B0); PG8_BAR; PG8_SCHED;
;       PG8_LDB(B1, 1, 1); PG8_STAGE(PG8_SB(1, 0), b3, voffB);
;       PG8_BAR; PG8_WAIT_L(0); PG8_MMA(0, 1, At, B1); PG8_BAR;
	s_add_u32 s80, s0, 0x40000
	s_addc_u32 s81, s1, 0
	s_mov_b32 m0, s14
	v_lshl_add_u64 v[140:141], s[80:81], 0, v[0:1]
	global_load_lds_dwordx4 v[140:141], off
	v_lshl_add_u64 v[140:141], s[80:81], 0, v[130:131]
	s_mov_b32 m0, s15
	s_nop 0
	global_load_lds_dwordx4 v[140:141], off
	s_waitcnt vmcnt(6)
	s_barrier
	v_mfma_f32_16x16x32_bf16 v[54:57], v[198:201], v[166:169], v[54:57]
	v_mfma_f32_16x16x32_bf16 v[66:69], v[206:209], v[166:169], v[66:69]
	v_mfma_f32_16x16x32_bf16 v[94:97], v[198:201], v[174:177], v[94:97]
	v_mfma_f32_16x16x32_bf16 v[106:109], v[206:209], v[174:177], v[106:109]
	v_mfma_f32_16x16x32_bf16 v[70:73], v[198:201], v[182:185], v[70:73]
	v_mfma_f32_16x16x32_bf16 v[78:81], v[206:209], v[182:185], v[78:81]
	v_mfma_f32_16x16x32_bf16 v[26:29], v[198:201], v[190:193], v[26:29]
	v_mfma_f32_16x16x32_bf16 v[34:37], v[206:209], v[190:193], v[34:37]
	v_mfma_f32_16x16x32_bf16 v[54:57], v[202:205], v[170:173], v[54:57]
	v_mfma_f32_16x16x32_bf16 v[66:69], v[210:213], v[170:173], v[66:69]
	v_mfma_f32_16x16x32_bf16 v[94:97], v[202:205], v[178:181], v[94:97]
	v_mfma_f32_16x16x32_bf16 v[106:109], v[210:213], v[178:181], v[106:109]
	v_mfma_f32_16x16x32_bf16 v[70:73], v[202:205], v[186:189], v[70:73]
	v_mfma_f32_16x16x32_bf16 v[78:81], v[210:213], v[186:189], v[78:81]
	v_mfma_f32_16x16x32_bf16 v[26:29], v[202:205], v[194:197], v[26:29]
	v_mfma_f32_16x16x32_bf16 v[34:37], v[210:213], v[194:197], v[34:37]
	v_or_b32_e32 v140, 0x18000, v146
	v_add_u32_e32 v148, 0x18400, v146
	v_add_u32_e32 v152, 0x18800, v146
	v_add_u32_e32 v156, 0x18c00, v146
	s_barrier
	ds_read_b128 v[140:143], v140
	ds_read_b128 v[148:151], v148
	ds_read_b128 v[152:155], v152
	ds_read_b128 v[156:159], v156
	s_add_u32 s30, s30, 0x40000
	s_addc_u32 s31, s31, 0
	s_mov_b32 m0, s16
	v_lshl_add_u64 v[198:199], s[30:31], 0, v[134:135]
	ds_read_b128 v[166:169], v145 offset:32768
	ds_read_b128 v[170:173], v145 offset:33792
	ds_read_b128 v[174:177], v145 offset:34816
	ds_read_b128 v[178:181], v145 offset:35840
	ds_read_b128 v[182:185], v145 offset:36864
	ds_read_b128 v[186:189], v145 offset:37888
	ds_read_b128 v[190:193], v145 offset:38912
	ds_read_b128 v[194:197], v145 offset:39936
	global_load_lds_dwordx4 v[198:199], off
	v_lshl_add_u64 v[198:199], s[30:31], 0, v[132:133]
	s_mov_b32 m0, s18
	s_nop 0
	global_load_lds_dwordx4 v[198:199], off
	s_barrier
	s_waitcnt lgkmcnt(0)
	s_waitcnt lgkmcnt(0)
	v_mfma_f32_16x16x32_bf16 v[118:121], v[140:143], v[166:169], v[118:121]
	v_mfma_f32_16x16x32_bf16 v[110:113], v[152:155], v[166:169], v[110:113]
	v_mfma_f32_16x16x32_bf16 v[90:93], v[140:143], v[174:177], v[90:93]
	v_mfma_f32_16x16x32_bf16 v[82:85], v[152:155], v[174:177], v[82:85]
	v_mfma_f32_16x16x32_bf16 v[62:65], v[140:143], v[182:185], v[62:65]
	v_mfma_f32_16x16x32_bf16 v[50:53], v[152:155], v[182:185], v[50:53]
	v_mfma_f32_16x16x32_bf16 v[42:45], v[140:143], v[190:193], v[42:45]
	v_mfma_f32_16x16x32_bf16 v[22:25], v[152:155], v[190:193], v[22:25]
	v_mfma_f32_16x16x32_bf16 v[118:121], v[148:151], v[170:173], v[118:121]
	v_mfma_f32_16x16x32_bf16 v[110:113], v[156:159], v[170:173], v[110:113]
	v_mfma_f32_16x16x32_bf16 v[90:93], v[148:151], v[178:181], v[90:93]
	v_mfma_f32_16x16x32_bf16 v[82:85], v[156:159], v[178:181], v[82:85]
	v_mfma_f32_16x16x32_bf16 v[62:65], v[148:151], v[186:189], v[62:65]
	v_mfma_f32_16x16x32_bf16 v[50:53], v[156:159], v[186:189], v[50:53]
	v_mfma_f32_16x16x32_bf16 v[42:45], v[148:151], v[194:197], v[42:45]
	v_mfma_f32_16x16x32_bf16 v[22:25], v[156:159], v[194:197], v[22:25]
	s_barrier
	v_or_b32_e32 v163, 0x1c000, v146
	s_mov_b32 m0, s8
	v_add_u32_e32 v165, 0x1c400, v146
	ds_read_b128 v[198:201], v163
	ds_read_b128 v[202:205], v165
	v_add_u32_e32 v163, 0x1c800, v146
	v_lshl_add_u64 v[160:161], v[160:161], 0, s[10:11]
	v_add_u32_e32 v165, 0x1cc00, v146
	ds_read_b128 v[206:209], v163
	ds_read_b128 v[210:213], v165
	global_load_lds_dwordx4 v[160:161], off
	v_lshl_add_u64 v[160:161], v[214:215], 0, s[10:11]
	s_mov_b32 m0, s9
	s_nop 0
	global_load_lds_dwordx4 v[160:161], off
	s_barrier
	s_waitcnt lgkmcnt(0)
	s_waitcnt lgkmcnt(0)
	v_mfma_f32_16x16x32_bf16 v[122:125], v[198:201], v[166:169], v[122:125]
	v_mfma_f32_16x16x32_bf16 v[126:129], v[206:209], v[166:169], v[126:129]
	v_mfma_f32_16x16x32_bf16 v[102:105], v[198:201], v[174:177], v[102:105]
	v_mfma_f32_16x16x32_bf16 v[114:117], v[206:209], v[174:177], v[114:117]
	v_mfma_f32_16x16x32_bf16 v[86:89], v[198:201], v[182:185], v[86:89]
	v_mfma_f32_16x16x32_bf16 v[98:101], v[206:209], v[182:185], v[98:101]
	v_mfma_f32_16x16x32_bf16 v[58:61], v[198:201], v[190:193], v[58:61]
	v_mfma_f32_16x16x32_bf16 v[74:77], v[206:209], v[190:193], v[74:77]
	v_mfma_f32_16x16x32_bf16 v[122:125], v[202:205], v[170:173], v[122:125]
	v_mfma_f32_16x16x32_bf16 v[126:129], v[210:213], v[170:173], v[126:129]
	v_mfma_f32_16x16x32_bf16 v[102:105], v[202:205], v[178:181], v[102:105]
	v_mfma_f32_16x16x32_bf16 v[114:117], v[210:213], v[178:181], v[114:117]
	v_mfma_f32_16x16x32_bf16 v[86:89], v[202:205], v[186:189], v[86:89]
	v_mfma_f32_16x16x32_bf16 v[98:101], v[210:213], v[186:189], v[98:101]
	v_mfma_f32_16x16x32_bf16 v[58:61], v[202:205], v[194:197], v[58:61]
	v_mfma_f32_16x16x32_bf16 v[74:77], v[210:213], v[194:197], v[74:77]
	s_mov_b32 m0, s19
	v_lshl_add_u64 v[160:161], v[216:217], 0, s[10:11]
	s_barrier
; DI bf16_t f2bf(float x) { unsigned u = __float_as_uint(x); u += 0x7fffu + ((u >> 16) & 1u); return (bf16_t)(u >> 16); }
; DI unsigned pack2(float lo, float hi) { f32x2_t v = {lo, hi}; return __builtin_bit_cast(unsigned, __builtin_convertvector(v, bf16x2_t)); }
; #define PG8_LAS __attribute__((address_space(3)))
; #define PG8_STAGE(bufoff, gbase, voff) do { _Pragma("unroll") for (int _i = 0; _i < 2; ++_i) \
;     __builtin_amdgcn_global_load_lds((const unsigned*)((const char*)(gbase) + (voff)[_i]), (PG8_LAS unsigned*)(lds + (bufoff) + ldsw + _i * 8192), 16, 0, 0); } while (0)
; #define PG8_LDA(dst, b, h) do { _Pragma("unroll") for (int m = 0; m < 4; ++m) _Pragma("unroll") for (int k = 0; k < 2; ++k) dst[m][k] = *(const PG8_LAS bf16x8*)(lds + PG8_SA(b, h) + aoff + m * 2048 + k * 1024); } while (0)
; #define PG8_WAIT_V(n) asm volatile("s_waitcnt vmcnt(" #n ")" ::: "memory")
;   DI void operator()(const f32x4 (&acc)[2][2][4][2], const Unit& u, int wr, int wc, int fr, int fq, const PG8_LAS float*) const {
;     const int row0 = u.pm * BM + wr * 64 + fr, col0 = u.pn * BM + wc * 32 + 8 * fq;
; #pragma unroll
;     for (int ai = 0; ai < 2; ++ai)
; #pragma unroll
;       for (int m = 0; m < 4; ++m) { const int row = row0 + ai * HALF + m * 16; bf16_t* rowp = dst + (size_t)row * DM + col0; float ss = 0.f;
; #pragma unroll
;         for (int bj = 0; bj < 2; ++bj) { const f32x4 v0 = acc[ai][bj][m][0] * coef, v1 = acc[ai][bj][m][1] * coef;
;           ss += v0[0] * v0[0] + v0[1] * v0[1] + v0[2] * v0[2] + v0[3] * v0[3] + v1[0] * v1[0] + v1[1] * v1[1] + v1[2] * v1[2] + v1[3] * v1[3];
;           u32x4 w; w.x = pack2(v0[0], v0[1]); w.y = pack2(v0[2], v0[3]); w.z = pack2(v1[0], v1[1]); w.w = pack2(v1[2], v1[3]);
;           *(u32x4*)(rowp + bj * HALF) = w; }
;         ss += __shfl_xor(ss, 16); ss += __shfl_xor(ss, 32);
;         if (fq == 0) ssq[(size_t)row * 16 + u.pn * 4 + wc] = f2bf(ss); }
; template <class Epi>
; DI void gemm_phase(const bf16_t* __restrict__ gA, const bf16_t* __restrict__ gBt, int M, int N, int K, const Epi& E, char* lds_generic) {
;     ...
;       PG8_BAR; PG8_WAIT_L(0); PG8_MMA(0, 1, At, B1); PG8_BAR;
;       PG8_LDA(At, 1, 1); PG8_STAGE(PG8_SA(1, 0), a3, voffA);
;       PG8_BAR; PG8_WAIT_L(0); PG8_MMA(1, 0, At, B0); PG8_BAR; PG8_SCHED;
;       PG8_STAGE(PG8_SB(1, 1), b3 + hstep, voffB);
;       PG8_WAIT_V(6); PG8_BAR; PG8_MMA(1, 1, At, B1); PG8_BAR;
	ds_read_b128 v[166:169], v145 offset:49152
	ds_read_b128 v[170:173], v145 offset:50176
	ds_read_b128 v[174:177], v145 offset:51200
	ds_read_b128 v[178:181], v145 offset:52224
	ds_read_b128 v[182:185], v145 offset:53248
	ds_read_b128 v[186:189], v145 offset:54272
	ds_read_b128 v[190:193], v145 offset:55296
	ds_read_b128 v[194:197], v145 offset:56320
	global_load_lds_dwordx4 v[160:161], off
	v_lshl_add_u64 v[160:161], v[218:219], 0, s[10:11]
	s_mov_b32 m0, s33
	s_nop 0
	global_load_lds_dwordx4 v[160:161], off
	s_barrier
	s_waitcnt lgkmcnt(0)
	s_waitcnt lgkmcnt(0)
	v_mfma_f32_16x16x32_bf16 v[38:41], v[140:143], v[166:169], v[38:41]
	v_mfma_f32_16x16x32_bf16 v[18:21], v[152:155], v[166:169], v[18:21]
	v_mfma_f32_16x16x32_bf16 v[10:13], v[140:143], v[174:177], v[10:13]
	v_mfma_f32_16x16x32_bf16 v[2:5], v[152:155], v[174:177], v[2:5]
	v_mfma_f32_16x16x32_bf16 v[46:49], v[140:143], v[182:185], v[46:49]
	v_mfma_f32_16x16x32_bf16 v[30:33], v[152:155], v[182:185], v[30:33]
	v_mfma_f32_16x16x32_bf16 v[14:17], v[140:143], v[190:193], v[14:17]
	v_mfma_f32_16x16x32_bf16 v[6:9], v[152:155], v[190:193], v[6:9]
	v_mfma_f32_16x16x32_bf16 v[38:41], v[148:151], v[170:173], v[38:41]
	v_mfma_f32_16x16x32_bf16 v[18:21], v[156:159], v[170:173], v[18:21]
	v_mfma_f32_16x16x32_bf16 v[10:13], v[148:151], v[178:181], v[10:13]
	v_mfma_f32_16x16x32_bf16 v[2:5], v[156:159], v[178:181], v[2:5]
	v_mfma_f32_16x16x32_bf16 v[46:49], v[148:151], v[186:189], v[46:49]
	v_mfma_f32_16x16x32_bf16 v[30:33], v[156:159], v[186:189], v[30:33]
	v_mfma_f32_16x16x32_bf16 v[14:17], v[148:151], v[194:197], v[14:17]
	v_mfma_f32_16x16x32_bf16 v[6:9], v[156:159], v[194:197], v[6:9]
	s_barrier
	s_add_u32 s0, s0, 0x40080
	s_addc_u32 s1, s1, 0
	s_mov_b32 m0, s35
	v_lshl_add_u64 v[140:141], s[0:1], 0, v[0:1]
	global_load_lds_dwordx4 v[140:141], off
	v_lshl_add_u64 v[140:141], s[0:1], 0, v[130:131]
	s_mov_b32 m0, s42
	s_nop 0
	global_load_lds_dwordx4 v[140:141], off
	s_waitcnt vmcnt(6)
	s_barrier
	v_mfma_f32_16x16x32_bf16 v[54:57], v[198:201], v[166:169], v[54:57]
	v_mfma_f32_16x16x32_bf16 v[66:69], v[206:209], v[166:169], v[66:69]
	v_mfma_f32_16x16x32_bf16 v[94:97], v[198:201], v[174:177], v[94:97]
	v_mfma_f32_16x16x32_bf16 v[106:109], v[206:209], v[174:177], v[106:109]
	v_mfma_f32_16x16x32_bf16 v[70:73], v[198:201], v[182:185], v[70:73]
	v_mfma_f32_16x16x32_bf16 v[78:81], v[206:209], v[182:185], v[78:81]
	v_mfma_f32_16x16x32_bf16 v[26:29], v[198:201], v[190:193], v[26:29]
	v_mfma_f32_16x16x32_bf16 v[34:37], v[206:209], v[190:193], v[34:37]
	v_mfma_f32_16x16x32_bf16 v[54:57], v[202:205], v[170:173], v[54:57]
	v_mfma_f32_16x16x32_bf16 v[66:69], v[210:213], v[170:173], v[66:69]
	v_mfma_f32_16x16x32_bf16 v[94:97], v[202:205], v[178:181], v[94:97]
	v_mfma_f32_16x16x32_bf16 v[106:109], v[210:213], v[178:181], v[106:109]
	v_mfma_f32_16x16x32_bf16 v[70:73], v[202:205], v[186:189], v[70:73]
	v_mfma_f32_16x16x32_bf16 v[78:81], v[210:213], v[186:189], v[78:81]
	v_mfma_f32_16x16x32_bf16 v[26:29], v[202:205], v[194:197], v[26:29]
	v_mfma_f32_16x16x32_bf16 v[34:37], v[210:213], v[194:197], v[34:37]
	s_add_i32 s60, s60, 2
	s_add_u32 s28, s28, 0x100
	s_addc_u32 s29, s29, 0
	s_add_u32 s58, s58, 0x100
	s_addc_u32 s59, s59, 0
	s_cmp_gt_u32 s60, 13
	s_barrier
	s_cbranch_scc0 .LBB0_511
	v_mul_f32_e32 v152, v119, v119
	v_fmac_f32_e32 v152, v118, v118
	v_fmac_f32_e32 v152, v120, v120
	v_cvt_pk_bf16_f32 v118, v118, v119
	v_cvt_pk_bf16_f32 v119, v120, v121
	v_mul_f32_e32 v120, v123, v123
	v_fmac_f32_e32 v120, v122, v122
	v_fmac_f32_e32 v120, v124, v124
	v_fmac_f32_e32 v152, v121, v121
	v_fmac_f32_e32 v120, v125, v125
	v_fmac_f32_e32 v152, v110, v110
	v_fmac_f32_e32 v120, v126, v126
	v_xor_b32_e32 v143, 16, v223
	v_fmac_f32_e32 v152, v111, v111
	v_fmac_f32_e32 v120, v127, v127
	v_cmp_lt_i32_e64 s[0:1], v143, v225
	v_fmac_f32_e32 v152, v112, v112
	v_fmac_f32_e32 v120, v128, v128
	v_cndmask_b32_e64 v143, v223, v143, s[0:1]
	v_fmac_f32_e32 v152, v113, v113
	v_fmac_f32_e32 v120, v129, v129
	v_lshlrev_b32_e32 v149, 2, v143
	v_add_f32_e32 v152, v152, v120
	ds_bpermute_b32 v153, v149, v152
	v_xor_b32_e32 v143, 32, v223
	v_cmp_lt_i32_e64 s[0:1], v143, v225
	v_lshl_add_u32 v142, s21, 8, v144
	v_cvt_pk_bf16_f32 v120, v110, v111
	v_cndmask_b32_e64 v143, v223, v143, s[0:1]
	v_lshlrev_b32_e32 v148, 2, v143
	s_waitcnt lgkmcnt(0)
	v_add_f32_e32 v110, v152, v153
	v_ashrrev_i32_e32 v143, 31, v142
	ds_bpermute_b32 v111, v148, v110
	v_lshl_or_b32 v140, s20, 8, v147
	v_lshlrev_b64 v[150:151], 11, v[142:143]
	v_ashrrev_i32_e32 v141, 31, v140
	v_lshl_add_u64 v[150:151], s[92:93], 0, v[150:151]
	s_lshl_b32 s0, s20, 2
	v_lshl_add_u64 v[150:151], v[140:141], 1, v[150:151]
	v_cvt_pk_bf16_f32 v121, v112, v113
	s_ashr_i32 s1, s0, 31
	global_store_dwordx4 v[150:151], v[118:121], off
	s_nop 1
	v_cvt_pk_bf16_f32 v118, v122, v123
	v_cvt_pk_bf16_f32 v119, v124, v125
	v_cvt_pk_bf16_f32 v120, v126, v127
	v_cvt_pk_bf16_f32 v121, v128, v129
	global_store_dwordx4 v[150:151], v[118:121], off offset:256
	s_and_saveexec_b64 s[28:29], s[36:37]
	s_cbranch_execz .LBB0_514
	s_waitcnt lgkmcnt(0)
	v_add_f32_e32 v110, v110, v111
	v_bfe_u32 v111, v110, 16, 1
	v_add3_u32 v112, v110, v111, s63
	v_lshlrev_b64 v[110:111], 5, v[142:143]
	v_lshl_add_u64 v[110:111], s[70:71], 0, v[110:111]
	v_lshl_add_u64 v[110:111], s[0:1], 1, v[110:111]
	s_lshl_b32 s76, s5, 1
	v_lshl_add_u64 v[110:111], v[110:111], 0, s[76:77]
	global_store_short_d16_hi v[110:111], v112, off

; #define PG8_STAGE(bufoff, gbase, voff) do { _Pragma("unroll") for (int _i = 0; _i < 2; ++_i) \
;     __builtin_amdgcn_global_load_lds((const unsigned*)((const char*)(gbase) + (voff)[_i]), (PG8_LAS unsigned*)(lds + (bufoff) + ldsw + _i * 8192), 16, 0, 0); } while (0)
; #define PG8_LDA(dst, b, h) do { _Pragma("unroll") for (int m = 0; m < 4; ++m) _Pragma("unroll") for (int k = 0; k < 2; ++k) dst[m][k] = *(const PG8_LAS bf16x8*)(lds + PG8_SA(b, h) + aoff + m * 2048 + k * 1024); } while (0)
; #define PG8_LDB(dst, b, h) do { _Pragma("unroll") for (int n = 0; n < 2; ++n) _Pragma("unroll") for (int k = 0; k < 2; ++k) dst[n][k] = *(const PG8_LAS bf16x8*)(lds + PG8_SB(b, h) + boff + n * 2048 + k * 1024); } while (0)
; #define PG8_MMA(ai, bj, At, Bt) do { __builtin_amdgcn_s_setprio(1); _Pragma("unroll") for (int m = 0; m < 4; ++m) _Pragma("unroll") for (int n = 0; n < 2; ++n) _Pragma("unroll") for (int k = 0; k < 2; ++k) \
;     acc[ai][bj][m][n] = __builtin_amdgcn_mfma_f32_16x16x32_bf16(Bt[n][k], At[m][k], acc[ai][bj][m][n], 0, 0, 0); __builtin_amdgcn_s_setprio(0); } while (0)
; #define PG8_WAIT_L(n) asm volatile("s_waitcnt lgkmcnt(" #n ")" ::: "memory")
; #define PG8_BAR __builtin_amdgcn_s_barrier()
; template <class Epi>
; DI void gemm_phase(const bf16_t* __restrict__ gA, const bf16_t* __restrict__ gBt, int M, int N, int K, const Epi& E, char* lds_generic) {
;     ...
;     const bool has_next = S.next(ui + 1, nxt);
;     const char* nA = has_next ? (const char*)gA + (size_t)nxt.pm * tstep : cA; const char* nB = has_next ? (const char*)gBt + (size_t)nxt.pn * tstep : cB;
;     for (int t = 0; t < nt; t += 2) {
;       const bool last = (t == nt - 2);
;       const char* a1 = cA + (size_t)(t + 1) * kstep;
;       const char* a2 = last ? nA : cA + (size_t)(t + 2) * kstep; const char* b2 = last ? nB : cB + (size_t)(t + 2) * kstep;
;       const char* a3 = a2 + kstep; const char* b3 = b2 + kstep;
;       PG8_LDB(B0, 0, 0); PG8_SCHED; PG8_LDA(At, 0, 0); PG8_STAGE(PG8_SA(1, 1), a1 + hstep, voffA);
;       PG8_WAIT_L(8); PG8_BAR; PG8_WAIT_L(0); PG8_MMA(0, 0, At, B0); PG8_BAR; PG8_SCHED;
;       PG8_LDB(B1, 0, 1); PG8_STAGE(PG8_SB(0, 0), b2, voffB);
;       PG8_BAR; PG8_WAIT_L(0); PG8_MMA(0, 1, At, B1); PG8_BAR;
;       PG8_LDA(At, 0, 1); PG8_STAGE(PG8_SA(0, 0), a2, voffA);
;       PG8_BAR; PG8_WAIT_L(0); PG8_MMA(1, 0, At, B0); PG8_BAR; PG8_SCHED;
.LBB0_604:
	s_ashr_i32 s87, s86, 31
	s_lshl_b64 s[20:21], s[86:87], 19
	s_add_u32 s88, s82, s20
	s_addc_u32 s89, s83, s21
	s_and_b64 s[20:21], s[38:39], exec
	s_cselect_b32 s20, s89, s29
	s_cselect_b32 s21, s88, s28
	s_ashr_i32 s27, s26, 31
	s_lshl_b64 s[22:23], s[26:27], 19
	s_add_u32 s90, s16, s22
	s_addc_u32 s91, s4, s23
	s_and_b64 s[22:23], s[38:39], exec
	s_cselect_b32 s27, s91, s31
	s_cselect_b32 s42, s90, s30
	s_add_u32 vcc_lo, s28, 0x40080
	s_addc_u32 vcc_hi, s29, 0
	s_add_u32 s87, s30, 0x100
	s_addc_u32 s22, s31, 0
	s_mov_b32 s23, -2
	v_or_b32_e32 v50, 0x10000, v155
	v_add_u32_e32 v146, 0x10400, v155
	v_add_u32_e32 v158, 0x10800, v155
	ds_read_b128 v[50:53], v50
	ds_read_b128 v[146:149], v146
	v_add_u32_e32 v163, 0x10c00, v155
	ds_read_b128 v[158:161], v158
	ds_read_b128 v[166:169], v163
	s_add_u32 s24, vcc_lo, 0xfffc0080
	s_addc_u32 s25, vcc_hi, -1
	s_cmp_eq_u32 s23, 12
	s_cselect_b32 s31, s20, s25
	s_cselect_b32 s30, s21, s24
	s_cselect_b32 s29, s27, s22
	s_cselect_b32 s28, s42, s87
	v_lshl_add_u64 v[202:203], vcc, 0, v[142:143]
	s_add_i32 m0, s72, 0xc000
	ds_read_b128 v[170:173], v154
	ds_read_b128 v[174:177], v154 offset:1024
	ds_read_b128 v[178:181], v154 offset:2048
	ds_read_b128 v[182:185], v154 offset:3072
	ds_read_b128 v[186:189], v154 offset:4096
	ds_read_b128 v[190:193], v154 offset:5120
	ds_read_b128 v[194:197], v154 offset:6144
	ds_read_b128 v[198:201], v154 offset:7168
	global_load_lds_dwordx4 v[202:203], off
	v_lshl_add_u64 v[202:203], vcc, 0, v[144:145]
	s_add_i32 m0, s72, 0xe000
	s_nop 0
	global_load_lds_dwordx4 v[202:203], off
	s_barrier
	s_waitcnt lgkmcnt(0)
	s_waitcnt lgkmcnt(0)
	v_mfma_f32_16x16x32_bf16 v[130:133], v[50:53], v[170:173], 0
	v_mfma_f32_16x16x32_bf16 v[122:125], v[158:161], v[170:173], 0
	v_mfma_f32_16x16x32_bf16 v[114:117], v[50:53], v[178:181], 0
	v_mfma_f32_16x16x32_bf16 v[106:109], v[158:161], v[178:181], 0
	v_mfma_f32_16x16x32_bf16 v[98:101], v[50:53], v[186:189], 0
	v_mfma_f32_16x16x32_bf16 v[90:93], v[158:161], v[186:189], 0
	v_mfma_f32_16x16x32_bf16 v[82:85], v[50:53], v[194:197], 0
	v_mfma_f32_16x16x32_bf16 v[74:77], v[158:161], v[194:197], 0
	v_mfma_f32_16x16x32_bf16 v[130:133], v[146:149], v[174:177], v[130:133]
	v_mfma_f32_16x16x32_bf16 v[122:125], v[166:169], v[174:177], v[122:125]
	v_mfma_f32_16x16x32_bf16 v[114:117], v[146:149], v[182:185], v[114:117]
	v_mfma_f32_16x16x32_bf16 v[106:109], v[166:169], v[182:185], v[106:109]
	v_mfma_f32_16x16x32_bf16 v[98:101], v[146:149], v[190:193], v[98:101]
	v_mfma_f32_16x16x32_bf16 v[90:93], v[166:169], v[190:193], v[90:93]
	v_mfma_f32_16x16x32_bf16 v[82:85], v[146:149], v[198:201], v[82:85]
	v_mfma_f32_16x16x32_bf16 v[74:77], v[166:169], v[198:201], v[74:77]
	s_barrier
	v_or_b32_e32 v163, 0x14000, v155
	s_mov_b32 m0, s14
	v_add_u32_e32 v165, 0x14400, v155
	ds_read_b128 v[202:205], v163
	ds_read_b128 v[206:209], v165
	v_add_u32_e32 v163, 0x14800, v155
	v_lshl_add_u64 v[218:219], s[28:29], 0, v[0:1]
	v_add_u32_e32 v165, 0x14c00, v155
	ds_read_b128 v[210:213], v163
	ds_read_b128 v[214:217], v165
	global_load_lds_dwordx4 v[218:219], off
	v_lshl_add_u64 v[220:221], s[28:29], 0, v[138:139]
	s_mov_b32 m0, s15
	s_nop 0
	global_load_lds_dwordx4 v[220:221], off
	s_barrier
	s_waitcnt lgkmcnt(0)
	s_waitcnt lgkmcnt(0)
	v_mfma_f32_16x16x32_bf16 v[126:129], v[202:205], v[170:173], 0
	v_mfma_f32_16x16x32_bf16 v[118:121], v[210:213], v[170:173], 0
	v_mfma_f32_16x16x32_bf16 v[110:113], v[202:205], v[178:181], 0
	v_mfma_f32_16x16x32_bf16 v[102:105], v[210:213], v[178:181], 0
	v_mfma_f32_16x16x32_bf16 v[94:97], v[202:205], v[186:189], 0
	v_mfma_f32_16x16x32_bf16 v[86:89], v[210:213], v[186:189], 0
	v_mfma_f32_16x16x32_bf16 v[78:81], v[202:205], v[194:197], 0
	v_mfma_f32_16x16x32_bf16 v[70:73], v[210:213], v[194:197], 0
	v_mfma_f32_16x16x32_bf16 v[126:129], v[206:209], v[174:177], v[126:129]
	v_mfma_f32_16x16x32_bf16 v[118:121], v[214:217], v[174:177], v[118:121]
	v_mfma_f32_16x16x32_bf16 v[110:113], v[206:209], v[182:185], v[110:113]
	v_mfma_f32_16x16x32_bf16 v[102:105], v[214:217], v[182:185], v[102:105]
	v_mfma_f32_16x16x32_bf16 v[94:97], v[206:209], v[190:193], v[94:97]
	v_mfma_f32_16x16x32_bf16 v[86:89], v[214:217], v[190:193], v[86:89]
	v_mfma_f32_16x16x32_bf16 v[78:81], v[206:209], v[198:201], v[78:81]
	v_mfma_f32_16x16x32_bf16 v[70:73], v[214:217], v[198:201], v[70:73]
	s_mov_b32 m0, s72
	v_lshl_add_u64 v[226:227], s[30:31], 0, v[134:135]
	s_barrier
	ds_read_b128 v[170:173], v154 offset:16384
	ds_read_b128 v[174:177], v154 offset:17408
	ds_read_b128 v[178:181], v154 offset:18432
	ds_read_b128 v[182:185], v154 offset:19456
	ds_read_b128 v[186:189], v154 offset:20480
	ds_read_b128 v[190:193], v154 offset:21504
	ds_read_b128 v[194:197], v154 offset:22528
	ds_read_b128 v[198:201], v154 offset:23552
	global_load_lds_dwordx4 v[226:227], off
	v_lshl_add_u64 v[228:229], s[30:31], 0, v[136:137]
	s_mov_b32 m0, s58
	s_nop 0
	global_load_lds_dwordx4 v[228:229], off
	s_barrier
	s_waitcnt lgkmcnt(0)
	s_waitcnt lgkmcnt(0)
	v_mfma_f32_16x16x32_bf16 v[66:69], v[50:53], v[170:173], 0
	v_mfma_f32_16x16x32_bf16 v[58:61], v[158:161], v[170:173], 0
	v_mfma_f32_16x16x32_bf16 v[46:49], v[50:53], v[178:181], 0
	v_mfma_f32_16x16x32_bf16 v[38:41], v[158:161], v[178:181], 0
	v_mfma_f32_16x16x32_bf16 v[30:33], v[50:53], v[186:189], 0
	v_mfma_f32_16x16x32_bf16 v[22:25], v[158:161], v[186:189], 0
	v_mfma_f32_16x16x32_bf16 v[14:17], v[50:53], v[194:197], 0
	v_mfma_f32_16x16x32_bf16 v[6:9], v[158:161], v[194:197], 0
	v_mfma_f32_16x16x32_bf16 v[66:69], v[146:149], v[174:177], v[66:69]
	v_mfma_f32_16x16x32_bf16 v[58:61], v[166:169], v[174:177], v[58:61]
	v_mfma_f32_16x16x32_bf16 v[46:49], v[146:149], v[182:185], v[46:49]
	v_mfma_f32_16x16x32_bf16 v[38:41], v[166:169], v[182:185], v[38:41]
	v_mfma_f32_16x16x32_bf16 v[30:33], v[146:149], v[190:193], v[30:33]
	v_mfma_f32_16x16x32_bf16 v[22:25], v[166:169], v[190:193], v[22:25]
	v_mfma_f32_16x16x32_bf16 v[14:17], v[146:149], v[198:201], v[14:17]
	v_mfma_f32_16x16x32_bf16 v[6:9], v[166:169], v[198:201], v[6:9]
	s_barrier
; #define PG8_STAGE(bufoff, gbase, voff) do { _Pragma("unroll") for (int _i = 0; _i < 2; ++_i) \
;     __builtin_amdgcn_global_load_lds((const unsigned*)((const char*)(gbase) + (voff)[_i]), (PG8_LAS unsigned*)(lds + (bufoff) + ldsw + _i * 8192), 16, 0, 0); } while (0)
; #define PG8_LDA(dst, b, h) do { _Pragma("unroll") for (int m = 0; m < 4; ++m) _Pragma("unroll") for (int k = 0; k < 2; ++k) dst[m][k] = *(const PG8_LAS bf16x8*)(lds + PG8_SA(b, h) + aoff + m * 2048 + k * 1024); } while (0)
; #define PG8_LDB(dst, b, h) do { _Pragma("unroll") for (int n = 0; n < 2; ++n) _Pragma("unroll") for (int k = 0; k < 2; ++k) dst[n][k] = *(const PG8_LAS bf16x8*)(lds + PG8_SB(b, h) + boff + n * 2048 + k * 1024); } while (0)
; #define PG8_MMA(ai, bj, At, Bt) do { __builtin_amdgcn_s_setprio(1); _Pragma("unroll") for (int m = 0; m < 4; ++m) _Pragma("unroll") for (int n = 0; n < 2; ++n) _Pragma("unroll") for (int k = 0; k < 2; ++k) \
;     acc[ai][bj][m][n] = __builtin_amdgcn_mfma_f32_16x16x32_bf16(Bt[n][k], At[m][k], acc[ai][bj][m][n], 0, 0, 0); __builtin_amdgcn_s_setprio(0); } while (0)
; #define PG8_WAIT_V(n) asm volatile("s_waitcnt vmcnt(" #n ")" ::: "memory")
; #define PG8_WAIT_L(n) asm volatile("s_waitcnt lgkmcnt(" #n ")" ::: "memory")
; #define PG8_BAR __builtin_amdgcn_s_barrier()
; template <class Epi>
; DI void gemm_phase(const bf16_t* __restrict__ gA, const bf16_t* __restrict__ gBt, int M, int N, int K, const Epi& E, char* lds_generic) {
;     ...
;     for (int t = 0; t < nt; t += 2) {
;       const bool last = (t == nt - 2);
;       const char* a1 = cA + (size_t)(t + 1) * kstep;
;       const char* a2 = last ? nA : cA + (size_t)(t + 2) * kstep; const char* b2 = last ? nB : cB + (size_t)(t + 2) * kstep;
;       const char* a3 = a2 + kstep; const char* b3 = b2 + kstep;
;       PG8_LDB(B0, 0, 0); PG8_SCHED; PG8_LDA(At, 0, 0); PG8_STAGE(PG8_SA(1, 1), a1 + hstep, voffA);
;       PG8_WAIT_L(8); PG8_BAR; PG8_WAIT_L(0); PG8_MMA(0, 0, At, B0); PG8_BAR; PG8_SCHED;
;       PG8_LDB(B1, 0, 1); PG8_STAGE(PG8_SB(0, 0), b2, voffB);
;       PG8_BAR; PG8_WAIT_L(0); PG8_MMA(0, 1, At, B1); PG8_BAR;
;       PG8_LDA(At, 0, 1); PG8_STAGE(PG8_SA(0, 0), a2, voffA);
;       PG8_BAR; PG8_WAIT_L(0); PG8_MMA(1, 0, At, B0); PG8_BAR; PG8_SCHED;
;       PG8_STAGE(PG8_SB(0, 1), b2 + hstep, voffB);
;       PG8_WAIT_V(6); PG8_BAR; PG8_MMA(1, 1, At, B1); PG8_BAR;
	s_add_u32 s24, s28, 0x40000
	s_addc_u32 s25, s29, 0
	s_mov_b32 m0, s59
	v_lshl_add_u64 v[50:51], s[24:25], 0, v[0:1]
	global_load_lds_dwordx4 v[50:51], off
	v_lshl_add_u64 v[50:51], s[24:25], 0, v[138:139]
	s_mov_b32 m0, s62
	s_nop 0
	global_load_lds_dwordx4 v[50:51], off
	s_waitcnt vmcnt(6)
	s_barrier
	v_mfma_f32_16x16x32_bf16 v[54:57], v[210:213], v[170:173], 0
	v_mfma_f32_16x16x32_bf16 v[42:45], v[202:205], v[178:181], 0
	v_mfma_f32_16x16x32_bf16 v[34:37], v[210:213], v[178:181], 0
	v_mfma_f32_16x16x32_bf16 v[26:29], v[202:205], v[186:189], 0
	v_mfma_f32_16x16x32_bf16 v[18:21], v[210:213], v[186:189], 0
	v_mfma_f32_16x16x32_bf16 v[10:13], v[202:205], v[194:197], 0
	v_mfma_f32_16x16x32_bf16 v[2:5], v[210:213], v[194:197], 0
	v_mfma_f32_16x16x32_bf16 v[50:53], v[202:205], v[170:173], 0
	v_mfma_f32_16x16x32_bf16 v[54:57], v[214:217], v[174:177], v[54:57]
	v_mfma_f32_16x16x32_bf16 v[42:45], v[206:209], v[182:185], v[42:45]
	v_mfma_f32_16x16x32_bf16 v[34:37], v[214:217], v[182:185], v[34:37]
	v_mfma_f32_16x16x32_bf16 v[26:29], v[206:209], v[190:193], v[26:29]
	v_mfma_f32_16x16x32_bf16 v[18:21], v[214:217], v[190:193], v[18:21]
	v_mfma_f32_16x16x32_bf16 v[10:13], v[206:209], v[198:201], v[10:13]
	v_mfma_f32_16x16x32_bf16 v[2:5], v[214:217], v[198:201], v[2:5]
	v_mfma_f32_16x16x32_bf16 v[50:53], v[206:209], v[174:177], v[50:53]
	v_or_b32_e32 v62, 0x18000, v155
	v_add_u32_e32 v146, 0x18400, v155
	v_add_u32_e32 v158, 0x18800, v155
	s_barrier
	s_branch .Lup605_p5
.LBB0_605:
	v_or_b32_e32 v50, 0x10000, v155
	v_add_u32_e32 v146, 0x10400, v155
	v_add_u32_e32 v158, 0x10800, v155
	ds_read_b128 v[50:53], v50
	ds_read_b128 v[146:149], v146
	v_add_u32_e32 v163, 0x10c00, v155
	ds_read_b128 v[158:161], v158
	ds_read_b128 v[166:169], v163
	s_add_u32 s24, vcc_lo, 0xfffc0080
	s_addc_u32 s25, vcc_hi, -1
	s_cmp_eq_u32 s23, 12
	s_cselect_b32 s31, s20, s25
	s_cselect_b32 s30, s21, s24
	s_cselect_b32 s29, s27, s22
	s_cselect_b32 s28, s42, s87
	v_lshl_add_u64 v[202:203], vcc, 0, v[142:143]
	s_add_i32 m0, s72, 0xc000
	ds_read_b128 v[170:173], v154
	ds_read_b128 v[174:177], v154 offset:1024
	ds_read_b128 v[178:181], v154 offset:2048
	ds_read_b128 v[182:185], v154 offset:3072
	ds_read_b128 v[186:189], v154 offset:4096
	ds_read_b128 v[190:193], v154 offset:5120
	ds_read_b128 v[194:197], v154 offset:6144
	ds_read_b128 v[198:201], v154 offset:7168
	global_load_lds_dwordx4 v[202:203], off
	v_lshl_add_u64 v[202:203], vcc, 0, v[144:145]
	s_add_i32 m0, s72, 0xe000
	s_nop 0
	global_load_lds_dwordx4 v[202:203], off
	s_barrier
	s_waitcnt lgkmcnt(0)
	s_waitcnt lgkmcnt(0)
	v_mfma_f32_16x16x32_bf16 v[130:133], v[50:53], v[170:173], v[130:133]
	v_mfma_f32_16x16x32_bf16 v[122:125], v[158:161], v[170:173], v[122:125]
	v_mfma_f32_16x16x32_bf16 v[114:117], v[50:53], v[178:181], v[114:117]
	v_mfma_f32_16x16x32_bf16 v[106:109], v[158:161], v[178:181], v[106:109]
	v_mfma_f32_16x16x32_bf16 v[98:101], v[50:53], v[186:189], v[98:101]
	v_mfma_f32_16x16x32_bf16 v[90:93], v[158:161], v[186:189], v[90:93]
	v_mfma_f32_16x16x32_bf16 v[82:85], v[50:53], v[194:197], v[82:85]
	v_mfma_f32_16x16x32_bf16 v[74:77], v[158:161], v[194:197], v[74:77]
	v_mfma_f32_16x16x32_bf16 v[130:133], v[146:149], v[174:177], v[130:133]
	v_mfma_f32_16x16x32_bf16 v[122:125], v[166:169], v[174:177], v[122:125]
	v_mfma_f32_16x16x32_bf16 v[114:117], v[146:149], v[182:185], v[114:117]
	v_mfma_f32_16x16x32_bf16 v[106:109], v[166:169], v[182:185], v[106:109]
	v_mfma_f32_16x16x32_bf16 v[98:101], v[146:149], v[190:193], v[98:101]
	v_mfma_f32_16x16x32_bf16 v[90:93], v[166:169], v[190:193], v[90:93]
	v_mfma_f32_16x16x32_bf16 v[82:85], v[146:149], v[198:201], v[82:85]
	v_mfma_f32_16x16x32_bf16 v[74:77], v[166:169], v[198:201], v[74:77]
	s_barrier
	v_or_b32_e32 v163, 0x14000, v155
	s_mov_b32 m0, s14
	v_add_u32_e32 v165, 0x14400, v155
	ds_read_b128 v[202:205], v163
	ds_read_b128 v[206:209], v165
	v_add_u32_e32 v163, 0x14800, v155
	v_lshl_add_u64 v[218:219], s[28:29], 0, v[0:1]
	v_add_u32_e32 v165, 0x14c00, v155
	ds_read_b128 v[210:213], v163
	ds_read_b128 v[214:217], v165
	global_load_lds_dwordx4 v[218:219], off
	v_lshl_add_u64 v[220:221], s[28:29], 0, v[138:139]
	s_mov_b32 m0, s15
	s_nop 0
	global_load_lds_dwordx4 v[220:221], off
	s_barrier
	s_waitcnt lgkmcnt(0)
	s_waitcnt lgkmcnt(0)
	v_mfma_f32_16x16x32_bf16 v[126:129], v[202:205], v[170:173], v[126:129]
	v_mfma_f32_16x16x32_bf16 v[118:121], v[210:213], v[170:173], v[118:121]
	v_mfma_f32_16x16x32_bf16 v[110:113], v[202:205], v[178:181], v[110:113]
	v_mfma_f32_16x16x32_bf16 v[102:105], v[210:213], v[178:181], v[102:105]
	v_mfma_f32_16x16x32_bf16 v[94:97], v[202:205], v[186:189], v[94:97]
	v_mfma_f32_16x16x32_bf16 v[86:89], v[210:213], v[186:189], v[86:89]
	v_mfma_f32_16x16x32_bf16 v[78:81], v[202:205], v[194:197], v[78:81]
	v_mfma_f32_16x16x32_bf16 v[70:73], v[210:213], v[194:197], v[70:73]
	v_mfma_f32_16x16x32_bf16 v[126:129], v[206:209], v[174:177], v[126:129]
	v_mfma_f32_16x16x32_bf16 v[118:121], v[214:217], v[174:177], v[118:121]
	v_mfma_f32_16x16x32_bf16 v[110:113], v[206:209], v[182:185], v[110:113]
	v_mfma_f32_16x16x32_bf16 v[102:105], v[214:217], v[182:185], v[102:105]
	v_mfma_f32_16x16x32_bf16 v[94:97], v[206:209], v[190:193], v[94:97]
	v_mfma_f32_16x16x32_bf16 v[86:89], v[214:217], v[190:193], v[86:89]
	v_mfma_f32_16x16x32_bf16 v[78:81], v[206:209], v[198:201], v[78:81]
	v_mfma_f32_16x16x32_bf16 v[70:73], v[214:217], v[198:201], v[70:73]
	s_mov_b32 m0, s72
	v_lshl_add_u64 v[226:227], s[30:31], 0, v[134:135]
	s_barrier
; #define PG8_STAGE(bufoff, gbase, voff) do { _Pragma("unroll") for (int _i = 0; _i < 2; ++_i) \
;     __builtin_amdgcn_global_load_lds((const unsigned*)((const char*)(gbase) + (voff)[_i]), (PG8_LAS unsigned*)(lds + (bufoff) + ldsw + _i * 8192), 16, 0, 0); } while (0)
; #define PG8_LDA(dst, b, h) do { _Pragma("unroll") for (int m = 0; m < 4; ++m) _Pragma("unroll") for (int k = 0; k < 2; ++k) dst[m][k] = *(const PG8_LAS bf16x8*)(lds + PG8_SA(b, h) + aoff + m * 2048 + k * 1024); } while (0)
; #define PG8_LDB(dst, b, h) do { _Pragma("unroll") for (int n = 0; n < 2; ++n) _Pragma("unroll") for (int k = 0; k < 2; ++k) dst[n][k] = *(const PG8_LAS bf16x8*)(lds + PG8_SB(b, h) + boff + n * 2048 + k * 1024); } while (0)
; #define PG8_MMA(ai, bj, At, Bt) do { __builtin_amdgcn_s_setprio(1); _Pragma("unroll") for (int m = 0; m < 4; ++m) _Pragma("unroll") for (int n = 0; n < 2; ++n) _Pragma("unroll") for (int k = 0; k < 2; ++k) \
;     acc[ai][bj][m][n] = __builtin_amdgcn_mfma_f32_16x16x32_bf16(Bt[n][k], At[m][k], acc[ai][bj][m][n], 0, 0, 0); __builtin_amdgcn_s_setprio(0); } while (0)
; #define PG8_WAIT_V(n) asm volatile("s_waitcnt vmcnt(" #n ")" ::: "memory")
; #define PG8_WAIT_L(n) asm volatile("s_waitcnt lgkmcnt(" #n ")" ::: "memory")
; #define PG8_BAR __builtin_amdgcn_s_barrier()
; #define PG8_SCHED __builtin_amdgcn_sched_barrier(0)
; template <class Epi>
; DI void gemm_phase(const bf16_t* __restrict__ gA, const bf16_t* __restrict__ gBt, int M, int N, int K, const Epi& E, char* lds_generic) {
;     ...
;       PG8_BAR; PG8_WAIT_L(0); PG8_MMA(1, 0, At, B0); PG8_BAR; PG8_SCHED;
;       PG8_STAGE(PG8_SB(0, 1), b2 + hstep, voffB);
;       PG8_WAIT_V(6); PG8_BAR; PG8_MMA(1, 1, At, B1); PG8_BAR;
;       PG8_LDB(B0, 1, 0); PG8_SCHED; PG8_LDA(At, 1, 0); PG8_STAGE(PG8_SA(0, 1), a2 + hstep, voffA);
;       PG8_WAIT_L(8); PG8_BAR; PG8_WAIT_L(0); PG8_MMA(0, 0, At, B0); PG8_BAR; PG8_SCHED;
	ds_read_b128 v[170:173], v154 offset:16384
	ds_read_b128 v[174:177], v154 offset:17408
	ds_read_b128 v[178:181], v154 offset:18432
	ds_read_b128 v[182:185], v154 offset:19456
	ds_read_b128 v[186:189], v154 offset:20480
	ds_read_b128 v[190:193], v154 offset:21504
	ds_read_b128 v[194:197], v154 offset:22528
	ds_read_b128 v[198:201], v154 offset:23552
	global_load_lds_dwordx4 v[226:227], off
	v_lshl_add_u64 v[228:229], s[30:31], 0, v[136:137]
	s_mov_b32 m0, s58
	s_nop 0
	global_load_lds_dwordx4 v[228:229], off
	s_barrier
	s_waitcnt lgkmcnt(0)
	s_waitcnt lgkmcnt(0)
	v_mfma_f32_16x16x32_bf16 v[66:69], v[50:53], v[170:173], v[66:69]
	v_mfma_f32_16x16x32_bf16 v[58:61], v[158:161], v[170:173], v[58:61]
	v_mfma_f32_16x16x32_bf16 v[46:49], v[50:53], v[178:181], v[46:49]
	v_mfma_f32_16x16x32_bf16 v[38:41], v[158:161], v[178:181], v[38:41]
	v_mfma_f32_16x16x32_bf16 v[30:33], v[50:53], v[186:189], v[30:33]
	v_mfma_f32_16x16x32_bf16 v[22:25], v[158:161], v[186:189], v[22:25]
	v_mfma_f32_16x16x32_bf16 v[14:17], v[50:53], v[194:197], v[14:17]
	v_mfma_f32_16x16x32_bf16 v[6:9], v[158:161], v[194:197], v[6:9]
	v_mfma_f32_16x16x32_bf16 v[66:69], v[146:149], v[174:177], v[66:69]
	v_mfma_f32_16x16x32_bf16 v[58:61], v[166:169], v[174:177], v[58:61]
	v_mfma_f32_16x16x32_bf16 v[46:49], v[146:149], v[182:185], v[46:49]
	v_mfma_f32_16x16x32_bf16 v[38:41], v[166:169], v[182:185], v[38:41]
	v_mfma_f32_16x16x32_bf16 v[30:33], v[146:149], v[190:193], v[30:33]
	v_mfma_f32_16x16x32_bf16 v[22:25], v[166:169], v[190:193], v[22:25]
	v_mfma_f32_16x16x32_bf16 v[14:17], v[146:149], v[198:201], v[14:17]
	v_mfma_f32_16x16x32_bf16 v[6:9], v[166:169], v[198:201], v[6:9]
	s_barrier
	s_add_u32 s24, s28, 0x40000
	s_addc_u32 s25, s29, 0
	s_mov_b32 m0, s59
	v_lshl_add_u64 v[50:51], s[24:25], 0, v[0:1]
	global_load_lds_dwordx4 v[50:51], off
	v_lshl_add_u64 v[50:51], s[24:25], 0, v[138:139]
	s_mov_b32 m0, s62
	s_nop 0
	global_load_lds_dwordx4 v[50:51], off
	s_waitcnt vmcnt(6)
	s_barrier
	v_mfma_f32_16x16x32_bf16 v[54:57], v[210:213], v[170:173], v[54:57]
	v_mfma_f32_16x16x32_bf16 v[42:45], v[202:205], v[178:181], v[42:45]
	v_mfma_f32_16x16x32_bf16 v[34:37], v[210:213], v[178:181], v[34:37]
	v_mfma_f32_16x16x32_bf16 v[26:29], v[202:205], v[186:189], v[26:29]
	v_mfma_f32_16x16x32_bf16 v[18:21], v[210:213], v[186:189], v[18:21]
	v_mfma_f32_16x16x32_bf16 v[10:13], v[202:205], v[194:197], v[10:13]
	v_mfma_f32_16x16x32_bf16 v[2:5], v[210:213], v[194:197], v[2:5]
	v_mfma_f32_16x16x32_bf16 v[50:53], v[202:205], v[170:173], v[62:65]
	v_mfma_f32_16x16x32_bf16 v[54:57], v[214:217], v[174:177], v[54:57]
	v_mfma_f32_16x16x32_bf16 v[42:45], v[206:209], v[182:185], v[42:45]
	v_mfma_f32_16x16x32_bf16 v[34:37], v[214:217], v[182:185], v[34:37]
	v_mfma_f32_16x16x32_bf16 v[26:29], v[206:209], v[190:193], v[26:29]
	v_mfma_f32_16x16x32_bf16 v[18:21], v[214:217], v[190:193], v[18:21]
	v_mfma_f32_16x16x32_bf16 v[10:13], v[206:209], v[198:201], v[10:13]
	v_mfma_f32_16x16x32_bf16 v[2:5], v[214:217], v[198:201], v[2:5]
	v_mfma_f32_16x16x32_bf16 v[50:53], v[206:209], v[174:177], v[50:53]
	v_or_b32_e32 v62, 0x18000, v155
	v_add_u32_e32 v146, 0x18400, v155
	v_add_u32_e32 v158, 0x18800, v155
	s_barrier
.Lup605_p5:
	ds_read_b128 v[62:65], v62
	ds_read_b128 v[146:149], v146
	v_add_u32_e32 v163, 0x18c00, v155
	ds_read_b128 v[158:161], v158
	ds_read_b128 v[166:169], v163
	s_add_u32 s24, s30, 0x40000
	s_addc_u32 s25, s31, 0
	s_mov_b32 m0, s7
	v_lshl_add_u64 v[202:203], s[24:25], 0, v[134:135]
	ds_read_b128 v[170:173], v154 offset:32768
	ds_read_b128 v[174:177], v154 offset:33792
	ds_read_b128 v[178:181], v154 offset:34816
	ds_read_b128 v[182:185], v154 offset:35840
	ds_read_b128 v[186:189], v154 offset:36864
	ds_read_b128 v[190:193], v154 offset:37888
	ds_read_b128 v[194:197], v154 offset:38912
	ds_read_b128 v[198:201], v154 offset:39936
	global_load_lds_dwordx4 v[202:203], off
	v_lshl_add_u64 v[202:203], s[24:25], 0, v[136:137]
	s_mov_b32 m0, s12
	s_nop 0
	global_load_lds_dwordx4 v[202:203], off
	s_barrier
	s_waitcnt lgkmcnt(0)
	s_waitcnt lgkmcnt(0)
	v_mfma_f32_16x16x32_bf16 v[130:133], v[62:65], v[170:173], v[130:133]
	v_mfma_f32_16x16x32_bf16 v[122:125], v[158:161], v[170:173], v[122:125]
	v_mfma_f32_16x16x32_bf16 v[114:117], v[62:65], v[178:181], v[114:117]
	v_mfma_f32_16x16x32_bf16 v[106:109], v[158:161], v[178:181], v[106:109]
	v_mfma_f32_16x16x32_bf16 v[98:101], v[62:65], v[186:189], v[98:101]
	v_mfma_f32_16x16x32_bf16 v[90:93], v[158:161], v[186:189], v[90:93]
	v_mfma_f32_16x16x32_bf16 v[82:85], v[62:65], v[194:197], v[82:85]
	v_mfma_f32_16x16x32_bf16 v[74:77], v[158:161], v[194:197], v[74:77]
	v_mfma_f32_16x16x32_bf16 v[130:133], v[146:149], v[174:177], v[130:133]
	v_mfma_f32_16x16x32_bf16 v[122:125], v[166:169], v[174:177], v[122:125]
	v_mfma_f32_16x16x32_bf16 v[114:117], v[146:149], v[182:185], v[114:117]
	v_mfma_f32_16x16x32_bf16 v[106:109], v[166:169], v[182:185], v[106:109]
	v_mfma_f32_16x16x32_bf16 v[98:101], v[146:149], v[190:193], v[98:101]
	v_mfma_f32_16x16x32_bf16 v[90:93], v[166:169], v[190:193], v[90:93]
	v_mfma_f32_16x16x32_bf16 v[82:85], v[146:149], v[198:201], v[82:85]
	v_mfma_f32_16x16x32_bf16 v[74:77], v[166:169], v[198:201], v[74:77]
	s_barrier
; #define PG8_STAGE(bufoff, gbase, voff) do { _Pragma("unroll") for (int _i = 0; _i < 2; ++_i) \
;     __builtin_amdgcn_global_load_lds((const unsigned*)((const char*)(gbase) + (voff)[_i]), (PG8_LAS unsigned*)(lds + (bufoff) + ldsw + _i * 8192), 16, 0, 0); } while (0)
; #define PG8_LDA(dst, b, h) do { _Pragma("unroll") for (int m = 0; m < 4; ++m) _Pragma("unroll") for (int k = 0; k < 2; ++k) dst[m][k] = *(const PG8_LAS bf16x8*)(lds + PG8_SA(b, h) + aoff + m * 2048 + k * 1024); } while (0)
; #define PG8_LDB(dst, b, h) do { _Pragma("unroll") for (int n = 0; n < 2; ++n) _Pragma("unroll") for (int k = 0; k < 2; ++k) dst[n][k] = *(const PG8_LAS bf16x8*)(lds + PG8_SB(b, h) + boff + n * 2048 + k * 1024); } while (0)
; #define PG8_MMA(ai, bj, At, Bt) do { __builtin_amdgcn_s_setprio(1); _Pragma("unroll") for (int m = 0; m < 4; ++m) _Pragma("unroll") for (int n = 0; n < 2; ++n) _Pragma("unroll") for (int k = 0; k < 2; ++k) \
;     acc[ai][bj][m][n] = __builtin_amdgcn_mfma_f32_16x16x32_bf16(Bt[n][k], At[m][k], acc[ai][bj][m][n], 0, 0, 0); __builtin_amdgcn_s_setprio(0); } while (0)
; #define PG8_WAIT_V(n) asm volatile("s_waitcnt vmcnt(" #n ")" ::: "memory")
; #define PG8_WAIT_L(n) asm volatile("s_waitcnt lgkmcnt(" #n ")" ::: "memory")
; #define PG8_BAR __builtin_amdgcn_s_barrier()
; #define PG8_SCHED __builtin_amdgcn_sched_barrier(0)
; #define PG8_RTAB_LOAD(var, unit) do { if constexpr (Epi::NEEDS_R) { var = *(const uint4*)(E.ssq + (size_t)((unit).pm * BM + (tid >> 1)) * 16 + (tid & 1) * 8); } } while (0)
; template <class Epi>
; DI void gemm_phase(const bf16_t* __restrict__ gA, const bf16_t* __restrict__ gBt, int M, int N, int K, const Epi& E, char* lds_generic) {
;     ...
;       PG8_LDB(B1, 1, 1); PG8_STAGE(PG8_SB(1, 0), b3, voffB);
;       PG8_BAR; PG8_WAIT_L(0); PG8_MMA(0, 1, At, B1); PG8_BAR;
;       PG8_LDA(At, 1, 1); PG8_STAGE(PG8_SA(1, 0), a3, voffA);
;       PG8_BAR; PG8_WAIT_L(0); PG8_MMA(1, 0, At, B0); PG8_BAR; PG8_SCHED;
;       PG8_STAGE(PG8_SB(1, 1), b3 + hstep, voffB);
;       PG8_WAIT_V(6); PG8_BAR; PG8_MMA(1, 1, At, B1); PG8_BAR;
;     }
;     uint4 rtn_ = {0u, 0u, 0u, 0u};
;     if (has_next) PG8_RTAB_LOAD(rtn_, nxt);
	v_or_b32_e32 v163, 0x1c000, v155
	s_mov_b32 m0, s13
	v_add_u32_e32 v165, 0x1c400, v155
	ds_read_b128 v[202:205], v163
	ds_read_b128 v[206:209], v165
	v_add_u32_e32 v163, 0x1c800, v155
	v_lshl_add_u64 v[218:219], v[218:219], 0, s[10:11]
	v_add_u32_e32 v165, 0x1cc00, v155
	ds_read_b128 v[210:213], v163
	ds_read_b128 v[214:217], v165
	global_load_lds_dwordx4 v[218:219], off
	v_lshl_add_u64 v[218:219], v[220:221], 0, s[10:11]
	s_mov_b32 m0, s35
	s_nop 0
	global_load_lds_dwordx4 v[218:219], off
	s_barrier
	s_waitcnt lgkmcnt(0)
	s_waitcnt lgkmcnt(0)
	v_mfma_f32_16x16x32_bf16 v[126:129], v[202:205], v[170:173], v[126:129]
	v_mfma_f32_16x16x32_bf16 v[118:121], v[210:213], v[170:173], v[118:121]
	v_mfma_f32_16x16x32_bf16 v[110:113], v[202:205], v[178:181], v[110:113]
	v_mfma_f32_16x16x32_bf16 v[102:105], v[210:213], v[178:181], v[102:105]
	v_mfma_f32_16x16x32_bf16 v[94:97], v[202:205], v[186:189], v[94:97]
	v_mfma_f32_16x16x32_bf16 v[86:89], v[210:213], v[186:189], v[86:89]
	v_mfma_f32_16x16x32_bf16 v[78:81], v[202:205], v[194:197], v[78:81]
	v_mfma_f32_16x16x32_bf16 v[70:73], v[210:213], v[194:197], v[70:73]
	v_mfma_f32_16x16x32_bf16 v[126:129], v[206:209], v[174:177], v[126:129]
	v_mfma_f32_16x16x32_bf16 v[118:121], v[214:217], v[174:177], v[118:121]
	v_mfma_f32_16x16x32_bf16 v[110:113], v[206:209], v[182:185], v[110:113]
	v_mfma_f32_16x16x32_bf16 v[102:105], v[214:217], v[182:185], v[102:105]
	v_mfma_f32_16x16x32_bf16 v[94:97], v[206:209], v[190:193], v[94:97]
	v_mfma_f32_16x16x32_bf16 v[86:89], v[214:217], v[190:193], v[86:89]
	v_mfma_f32_16x16x32_bf16 v[78:81], v[206:209], v[198:201], v[78:81]
	v_mfma_f32_16x16x32_bf16 v[70:73], v[214:217], v[198:201], v[70:73]
	s_mov_b32 m0, s53
	v_lshl_add_u64 v[218:219], v[226:227], 0, s[10:11]
	s_barrier
	ds_read_b128 v[170:173], v154 offset:49152
	ds_read_b128 v[174:177], v154 offset:50176
	ds_read_b128 v[178:181], v154 offset:51200
	ds_read_b128 v[182:185], v154 offset:52224
	ds_read_b128 v[186:189], v154 offset:53248
	ds_read_b128 v[190:193], v154 offset:54272
	ds_read_b128 v[194:197], v154 offset:55296
	ds_read_b128 v[198:201], v154 offset:56320
	global_load_lds_dwordx4 v[218:219], off
	v_lshl_add_u64 v[218:219], v[228:229], 0, s[10:11]
	s_mov_b32 m0, s74
	s_nop 0
	global_load_lds_dwordx4 v[218:219], off
	s_barrier
	s_waitcnt lgkmcnt(0)
	s_waitcnt lgkmcnt(0)
	v_mfma_f32_16x16x32_bf16 v[66:69], v[62:65], v[170:173], v[66:69]
	v_mfma_f32_16x16x32_bf16 v[58:61], v[158:161], v[170:173], v[58:61]
	v_mfma_f32_16x16x32_bf16 v[46:49], v[62:65], v[178:181], v[46:49]
	v_mfma_f32_16x16x32_bf16 v[38:41], v[158:161], v[178:181], v[38:41]
	v_mfma_f32_16x16x32_bf16 v[30:33], v[62:65], v[186:189], v[30:33]
	v_mfma_f32_16x16x32_bf16 v[22:25], v[158:161], v[186:189], v[22:25]
	v_mfma_f32_16x16x32_bf16 v[14:17], v[62:65], v[194:197], v[14:17]
	v_mfma_f32_16x16x32_bf16 v[6:9], v[158:161], v[194:197], v[6:9]
	v_mfma_f32_16x16x32_bf16 v[66:69], v[146:149], v[174:177], v[66:69]
	v_mfma_f32_16x16x32_bf16 v[58:61], v[166:169], v[174:177], v[58:61]
	v_mfma_f32_16x16x32_bf16 v[46:49], v[146:149], v[182:185], v[46:49]
	v_mfma_f32_16x16x32_bf16 v[38:41], v[166:169], v[182:185], v[38:41]
	v_mfma_f32_16x16x32_bf16 v[30:33], v[146:149], v[190:193], v[30:33]
	v_mfma_f32_16x16x32_bf16 v[22:25], v[166:169], v[190:193], v[22:25]
	v_mfma_f32_16x16x32_bf16 v[14:17], v[146:149], v[198:201], v[14:17]
	v_mfma_f32_16x16x32_bf16 v[6:9], v[166:169], v[198:201], v[6:9]
	s_barrier
	s_add_u32 s24, s28, 0x40080
	s_addc_u32 s25, s29, 0
	s_mov_b32 m0, s60
	v_lshl_add_u64 v[62:63], s[24:25], 0, v[0:1]
	global_load_lds_dwordx4 v[62:63], off
	v_lshl_add_u64 v[62:63], s[24:25], 0, v[138:139]
	s_mov_b32 m0, s6
	s_nop 0
	global_load_lds_dwordx4 v[62:63], off
	s_waitcnt vmcnt(6)
	s_barrier
	v_mfma_f32_16x16x32_bf16 v[50:53], v[202:205], v[170:173], v[50:53]
	v_mfma_f32_16x16x32_bf16 v[62:65], v[206:209], v[174:177], v[50:53]
	v_mfma_f32_16x16x32_bf16 v[50:53], v[210:213], v[170:173], v[54:57]
	v_mfma_f32_16x16x32_bf16 v[42:45], v[202:205], v[178:181], v[42:45]
	v_mfma_f32_16x16x32_bf16 v[34:37], v[210:213], v[178:181], v[34:37]
	v_mfma_f32_16x16x32_bf16 v[26:29], v[202:205], v[186:189], v[26:29]
	v_mfma_f32_16x16x32_bf16 v[18:21], v[210:213], v[186:189], v[18:21]
	v_mfma_f32_16x16x32_bf16 v[10:13], v[202:205], v[194:197], v[10:13]
	v_mfma_f32_16x16x32_bf16 v[2:5], v[210:213], v[194:197], v[2:5]
	v_mfma_f32_16x16x32_bf16 v[54:57], v[214:217], v[174:177], v[50:53]
	v_mfma_f32_16x16x32_bf16 v[42:45], v[206:209], v[182:185], v[42:45]
	v_mfma_f32_16x16x32_bf16 v[34:37], v[214:217], v[182:185], v[34:37]
	v_mfma_f32_16x16x32_bf16 v[26:29], v[206:209], v[190:193], v[26:29]
	v_mfma_f32_16x16x32_bf16 v[18:21], v[214:217], v[190:193], v[18:21]
	v_mfma_f32_16x16x32_bf16 v[10:13], v[206:209], v[198:201], v[10:13]
	v_mfma_f32_16x16x32_bf16 v[2:5], v[214:217], v[198:201], v[2:5]
	s_add_i32 s23, s23, 2
	s_add_u32 vcc_lo, vcc_lo, 0x100
	s_addc_u32 vcc_hi, vcc_hi, 0
	s_add_u32 s87, s87, 0x100
	s_addc_u32 s22, s22, 0
	s_cmp_gt_u32 s23, 13
	s_barrier
	s_cbranch_scc0 .LBB0_605
	v_mov_b32_e32 v50, 0
	s_and_b64 vcc, exec, s[38:39]
	v_mov_b32_e32 v51, 0
	v_mov_b32_e32 v52, 0
	v_mov_b32_e32 v53, 0
	s_cbranch_vccz .LBB0_608
	v_lshl_add_u32 v50, s86, 8, v150
	v_ashrrev_i32_e32 v51, 31, v50
	v_lshlrev_b64 v[50:51], 5, v[50:51]
	v_lshl_add_u64 v[50:51], v[140:141], 0, v[50:51]
	global_load_dwordx4 v[50:53], v[50:51], off

; #define PG8_STAGE(bufoff, gbase, voff) do { _Pragma("unroll") for (int _i = 0; _i < 2; ++_i) \
;     __builtin_amdgcn_global_load_lds((const unsigned*)((const char*)(gbase) + (voff)[_i]), (PG8_LAS unsigned*)(lds + (bufoff) + ldsw + _i * 8192), 16, 0, 0); } while (0)
; #define PG8_LDA(dst, b, h) do { _Pragma("unroll") for (int m = 0; m < 4; ++m) _Pragma("unroll") for (int k = 0; k < 2; ++k) dst[m][k] = *(const PG8_LAS bf16x8*)(lds + PG8_SA(b, h) + aoff + m * 2048 + k * 1024); } while (0)
; #define PG8_LDB(dst, b, h) do { _Pragma("unroll") for (int n = 0; n < 2; ++n) _Pragma("unroll") for (int k = 0; k < 2; ++k) dst[n][k] = *(const PG8_LAS bf16x8*)(lds + PG8_SB(b, h) + boff + n * 2048 + k * 1024); } while (0)
; #define PG8_MMA(ai, bj, At, Bt) do { __builtin_amdgcn_s_setprio(1); _Pragma("unroll") for (int m = 0; m < 4; ++m) _Pragma("unroll") for (int n = 0; n < 2; ++n) _Pragma("unroll") for (int k = 0; k < 2; ++k) \
;     acc[ai][bj][m][n] = __builtin_amdgcn_mfma_f32_16x16x32_bf16(Bt[n][k], At[m][k], acc[ai][bj][m][n], 0, 0, 0); __builtin_amdgcn_s_setprio(0); } while (0)
; #define PG8_WAIT_L(n) asm volatile("s_waitcnt lgkmcnt(" #n ")" ::: "memory")
; #define PG8_BAR __builtin_amdgcn_s_barrier()
; #define PG8_SCHED __builtin_amdgcn_sched_barrier(0)
; template <class Epi>
; DI void gemm_phase(const bf16_t* __restrict__ gA, const bf16_t* __restrict__ gBt, int M, int N, int K, const Epi& E, char* lds_generic) {
;     ...
;     for (int t = 0; t < nt; t += 2) {
;       const bool last = (t == nt - 2);
;       const char* a1 = cA + (size_t)(t + 1) * kstep;
;       const char* a2 = last ? nA : cA + (size_t)(t + 2) * kstep; const char* b2 = last ? nB : cB + (size_t)(t + 2) * kstep;
;       const char* a3 = a2 + kstep; const char* b3 = b2 + kstep;
;       PG8_LDB(B0, 0, 0); PG8_SCHED; PG8_LDA(At, 0, 0); PG8_STAGE(PG8_SA(1, 1), a1 + hstep, voffA);
;       PG8_WAIT_L(8); PG8_BAR; PG8_WAIT_L(0); PG8_MMA(0, 0, At, B0); PG8_BAR; PG8_SCHED;
;       PG8_LDB(B1, 0, 1); PG8_STAGE(PG8_SB(0, 0), b2, voffB);
;       PG8_BAR; PG8_WAIT_L(0); PG8_MMA(0, 1, At, B1); PG8_BAR;
;       PG8_LDA(At, 0, 1); PG8_STAGE(PG8_SA(0, 0), a2, voffA);
;       PG8_BAR; PG8_WAIT_L(0); PG8_MMA(1, 0, At, B0); PG8_BAR; PG8_SCHED;
.LBB0_684:
	v_or_b32_e32 v140, 0x10000, v146
	v_add_u32_e32 v148, 0x10400, v146
	v_add_u32_e32 v152, 0x10800, v146
	v_add_u32_e32 v156, 0x10c00, v146
	ds_read_b128 v[140:143], v140
	ds_read_b128 v[148:151], v148
	ds_read_b128 v[152:155], v152
	ds_read_b128 v[156:159], v156
	s_add_u32 s28, s88, 0x100
	s_addc_u32 s29, s89, 0
	s_cmp_eq_u32 s23, 40
	s_cselect_b32 s91, s87, s29
	s_cselect_b32 s90, s86, s28
	s_cselect_b32 s31, s1, s22
	s_cselect_b32 s30, s0, s21
	v_lshl_add_u64 v[160:161], s[88:89], 0, v[136:137]
	s_add_i32 m0, s12, 0xc000
	ds_read_b128 v[166:169], v145
	ds_read_b128 v[170:173], v145 offset:1024
	ds_read_b128 v[174:177], v145 offset:2048
	ds_read_b128 v[178:181], v145 offset:3072
	ds_read_b128 v[182:185], v145 offset:4096
	ds_read_b128 v[186:189], v145 offset:5120
	ds_read_b128 v[190:193], v145 offset:6144
	ds_read_b128 v[194:197], v145 offset:7168
	global_load_lds_dwordx4 v[160:161], off
	v_lshl_add_u64 v[160:161], s[88:89], 0, v[138:139]
	s_add_i32 m0, s12, 0xe000
	s_nop 0
	global_load_lds_dwordx4 v[160:161], off
	s_barrier
	s_waitcnt lgkmcnt(0)
	s_waitcnt lgkmcnt(0)
	v_mfma_f32_16x16x32_bf16 v[126:129], v[140:143], v[166:169], v[126:129]
	v_mfma_f32_16x16x32_bf16 v[122:125], v[152:155], v[166:169], v[122:125]
	v_mfma_f32_16x16x32_bf16 v[110:113], v[140:143], v[174:177], v[110:113]
	v_mfma_f32_16x16x32_bf16 v[106:109], v[152:155], v[174:177], v[106:109]
	v_mfma_f32_16x16x32_bf16 v[94:97], v[140:143], v[182:185], v[94:97]
	v_mfma_f32_16x16x32_bf16 v[90:93], v[152:155], v[182:185], v[90:93]
	v_mfma_f32_16x16x32_bf16 v[78:81], v[140:143], v[190:193], v[78:81]
	v_mfma_f32_16x16x32_bf16 v[74:77], v[152:155], v[190:193], v[74:77]
	v_mfma_f32_16x16x32_bf16 v[126:129], v[148:151], v[170:173], v[126:129]
	v_mfma_f32_16x16x32_bf16 v[122:125], v[156:159], v[170:173], v[122:125]
	v_mfma_f32_16x16x32_bf16 v[110:113], v[148:151], v[178:181], v[110:113]
	v_mfma_f32_16x16x32_bf16 v[106:109], v[156:159], v[178:181], v[106:109]
	v_mfma_f32_16x16x32_bf16 v[94:97], v[148:151], v[186:189], v[94:97]
	v_mfma_f32_16x16x32_bf16 v[90:93], v[156:159], v[186:189], v[90:93]
	v_mfma_f32_16x16x32_bf16 v[78:81], v[148:151], v[194:197], v[78:81]
	v_mfma_f32_16x16x32_bf16 v[74:77], v[156:159], v[194:197], v[74:77]
	s_barrier
	v_or_b32_e32 v160, 0x14000, v146
	v_add_u32_e32 v161, 0x14400, v146
	ds_read_b128 v[198:201], v160
	ds_read_b128 v[202:205], v161
	v_add_u32_e32 v160, 0x14800, v146
	v_add_u32_e32 v161, 0x14c00, v146
	s_mov_b32 m0, s13
	ds_read_b128 v[206:209], v160
	ds_read_b128 v[210:213], v161
	v_lshl_add_u64 v[160:161], s[30:31], 0, v[0:1]
	global_load_lds_dwordx4 v[160:161], off
	v_lshl_add_u64 v[214:215], s[30:31], 0, v[134:135]
	s_mov_b32 m0, s14
	s_nop 0
	global_load_lds_dwordx4 v[214:215], off
	s_barrier
	s_waitcnt lgkmcnt(0)
	s_waitcnt lgkmcnt(0)
	v_mfma_f32_16x16x32_bf16 v[118:121], v[198:201], v[166:169], v[118:121]
	v_mfma_f32_16x16x32_bf16 v[114:117], v[206:209], v[166:169], v[114:117]
	v_mfma_f32_16x16x32_bf16 v[102:105], v[198:201], v[174:177], v[102:105]
	v_mfma_f32_16x16x32_bf16 v[98:101], v[206:209], v[174:177], v[98:101]
	v_mfma_f32_16x16x32_bf16 v[86:89], v[198:201], v[182:185], v[86:89]
	v_mfma_f32_16x16x32_bf16 v[82:85], v[206:209], v[182:185], v[82:85]
	v_mfma_f32_16x16x32_bf16 v[70:73], v[198:201], v[190:193], v[70:73]
	v_mfma_f32_16x16x32_bf16 v[66:69], v[206:209], v[190:193], v[66:69]
	v_mfma_f32_16x16x32_bf16 v[118:121], v[202:205], v[170:173], v[118:121]
	v_mfma_f32_16x16x32_bf16 v[114:117], v[210:213], v[170:173], v[114:117]
	v_mfma_f32_16x16x32_bf16 v[102:105], v[202:205], v[178:181], v[102:105]
	v_mfma_f32_16x16x32_bf16 v[98:101], v[210:213], v[178:181], v[98:101]
	v_mfma_f32_16x16x32_bf16 v[86:89], v[202:205], v[186:189], v[86:89]
	v_mfma_f32_16x16x32_bf16 v[82:85], v[210:213], v[186:189], v[82:85]
	v_mfma_f32_16x16x32_bf16 v[70:73], v[202:205], v[194:197], v[70:73]
	v_mfma_f32_16x16x32_bf16 v[66:69], v[210:213], v[194:197], v[66:69]
	s_mov_b32 m0, s12
	v_lshl_add_u64 v[216:217], s[90:91], 0, v[130:131]
	s_barrier
	ds_read_b128 v[166:169], v145 offset:16384
	ds_read_b128 v[170:173], v145 offset:17408
	ds_read_b128 v[174:177], v145 offset:18432
	ds_read_b128 v[178:181], v145 offset:19456
	ds_read_b128 v[182:185], v145 offset:20480
	ds_read_b128 v[186:189], v145 offset:21504
	ds_read_b128 v[190:193], v145 offset:22528
	ds_read_b128 v[194:197], v145 offset:23552
	global_load_lds_dwordx4 v[216:217], off
	v_lshl_add_u64 v[218:219], s[90:91], 0, v[132:133]
	s_mov_b32 m0, s15
	s_nop 0
	global_load_lds_dwordx4 v[218:219], off
	s_barrier
	s_waitcnt lgkmcnt(0)
	s_waitcnt lgkmcnt(0)
	v_mfma_f32_16x16x32_bf16 v[62:65], v[140:143], v[166:169], v[62:65]
	v_mfma_f32_16x16x32_bf16 v[58:61], v[152:155], v[166:169], v[58:61]
	v_mfma_f32_16x16x32_bf16 v[46:49], v[140:143], v[174:177], v[46:49]
	v_mfma_f32_16x16x32_bf16 v[42:45], v[152:155], v[174:177], v[42:45]
	v_mfma_f32_16x16x32_bf16 v[30:33], v[140:143], v[182:185], v[30:33]
	v_mfma_f32_16x16x32_bf16 v[26:29], v[152:155], v[182:185], v[26:29]
	v_mfma_f32_16x16x32_bf16 v[14:17], v[140:143], v[190:193], v[14:17]
	v_mfma_f32_16x16x32_bf16 v[10:13], v[152:155], v[190:193], v[10:13]
	v_mfma_f32_16x16x32_bf16 v[62:65], v[148:151], v[170:173], v[62:65]
	v_mfma_f32_16x16x32_bf16 v[58:61], v[156:159], v[170:173], v[58:61]
	v_mfma_f32_16x16x32_bf16 v[46:49], v[148:151], v[178:181], v[46:49]
	v_mfma_f32_16x16x32_bf16 v[42:45], v[156:159], v[178:181], v[42:45]
	v_mfma_f32_16x16x32_bf16 v[30:33], v[148:151], v[186:189], v[30:33]
	v_mfma_f32_16x16x32_bf16 v[26:29], v[156:159], v[186:189], v[26:29]
	v_mfma_f32_16x16x32_bf16 v[14:17], v[148:151], v[194:197], v[14:17]
	v_mfma_f32_16x16x32_bf16 v[10:13], v[156:159], v[194:197], v[10:13]
	s_barrier
; #define PG8_STAGE(bufoff, gbase, voff) do { _Pragma("unroll") for (int _i = 0; _i < 2; ++_i) \
;     __builtin_amdgcn_global_load_lds((const unsigned*)((const char*)(gbase) + (voff)[_i]), (PG8_LAS unsigned*)(lds + (bufoff) + ldsw + _i * 8192), 16, 0, 0); } while (0)
; #define PG8_LDA(dst, b, h) do { _Pragma("unroll") for (int m = 0; m < 4; ++m) _Pragma("unroll") for (int k = 0; k < 2; ++k) dst[m][k] = *(const PG8_LAS bf16x8*)(lds + PG8_SA(b, h) + aoff + m * 2048 + k * 1024); } while (0)
; #define PG8_LDB(dst, b, h) do { _Pragma("unroll") for (int n = 0; n < 2; ++n) _Pragma("unroll") for (int k = 0; k < 2; ++k) dst[n][k] = *(const PG8_LAS bf16x8*)(lds + PG8_SB(b, h) + boff + n * 2048 + k * 1024); } while (0)
; #define PG8_MMA(ai, bj, At, Bt) do { __builtin_amdgcn_s_setprio(1); _Pragma("unroll") for (int m = 0; m < 4; ++m) _Pragma("unroll") for (int n = 0; n < 2; ++n) _Pragma("unroll") for (int k = 0; k < 2; ++k) \
;     acc[ai][bj][m][n] = __builtin_amdgcn_mfma_f32_16x16x32_bf16(Bt[n][k], At[m][k], acc[ai][bj][m][n], 0, 0, 0); __builtin_amdgcn_s_setprio(0); } while (0)
; #define PG8_WAIT_V(n) asm volatile("s_waitcnt vmcnt(" #n ")" ::: "memory")
; #define PG8_WAIT_L(n) asm volatile("s_waitcnt lgkmcnt(" #n ")" ::: "memory")
; #define PG8_BAR __builtin_amdgcn_s_barrier()
; #define PG8_SCHED __builtin_amdgcn_sched_barrier(0)
; template <class Epi>
; DI void gemm_phase(const bf16_t* __restrict__ gA, const bf16_t* __restrict__ gBt, int M, int N, int K, const Epi& E, char* lds_generic) {
;     ...
;       PG8_STAGE(PG8_SB(0, 1), b2 + hstep, voffB);
;       PG8_WAIT_V(6); PG8_BAR; PG8_MMA(1, 1, At, B1); PG8_BAR;
;       PG8_LDB(B0, 1, 0); PG8_SCHED; PG8_LDA(At, 1, 0); PG8_STAGE(PG8_SA(0, 1), a2 + hstep, voffA);
;       PG8_WAIT_L(8); PG8_BAR; PG8_WAIT_L(0); PG8_MMA(0, 0, At, B0); PG8_BAR; PG8_SCHED;
;       PG8_LDB(B1, 1, 1); PG8_STAGE(PG8_SB(1, 0), b3, voffB);
;       PG8_BAR; PG8_WAIT_L(0); PG8_MMA(0, 1, At, B1); PG8_BAR;
;       PG8_LDA(At, 1, 1); PG8_STAGE(PG8_SA(1, 0), a3, voffA);
	s_add_u32 s24, s30, 0xb0000
	s_addc_u32 s25, s31, 0
	s_mov_b32 m0, s18
	v_lshl_add_u64 v[140:141], s[24:25], 0, v[0:1]
	global_load_lds_dwordx4 v[140:141], off
	v_lshl_add_u64 v[140:141], s[24:25], 0, v[134:135]
	s_mov_b32 m0, s35
	s_nop 0
	global_load_lds_dwordx4 v[140:141], off
	s_waitcnt vmcnt(6)
	s_barrier
	v_mfma_f32_16x16x32_bf16 v[54:57], v[198:201], v[166:169], v[54:57]
	v_mfma_f32_16x16x32_bf16 v[50:53], v[206:209], v[166:169], v[50:53]
	v_mfma_f32_16x16x32_bf16 v[38:41], v[198:201], v[174:177], v[38:41]
	v_mfma_f32_16x16x32_bf16 v[34:37], v[206:209], v[174:177], v[34:37]
	v_mfma_f32_16x16x32_bf16 v[22:25], v[198:201], v[182:185], v[22:25]
	v_mfma_f32_16x16x32_bf16 v[18:21], v[206:209], v[182:185], v[18:21]
	v_mfma_f32_16x16x32_bf16 v[6:9], v[198:201], v[190:193], v[6:9]
	v_mfma_f32_16x16x32_bf16 v[2:5], v[206:209], v[190:193], v[2:5]
	v_mfma_f32_16x16x32_bf16 v[54:57], v[202:205], v[170:173], v[54:57]
	v_mfma_f32_16x16x32_bf16 v[50:53], v[210:213], v[170:173], v[50:53]
	v_mfma_f32_16x16x32_bf16 v[38:41], v[202:205], v[178:181], v[38:41]
	v_mfma_f32_16x16x32_bf16 v[34:37], v[210:213], v[178:181], v[34:37]
	v_mfma_f32_16x16x32_bf16 v[22:25], v[202:205], v[186:189], v[22:25]
	v_mfma_f32_16x16x32_bf16 v[18:21], v[210:213], v[186:189], v[18:21]
	v_mfma_f32_16x16x32_bf16 v[6:9], v[202:205], v[194:197], v[6:9]
	v_mfma_f32_16x16x32_bf16 v[2:5], v[210:213], v[194:197], v[2:5]
	v_or_b32_e32 v140, 0x18000, v146
	v_add_u32_e32 v148, 0x18400, v146
	v_add_u32_e32 v152, 0x18800, v146
	v_add_u32_e32 v156, 0x18c00, v146
	s_barrier
	ds_read_b128 v[140:143], v140
	ds_read_b128 v[148:151], v148
	ds_read_b128 v[152:155], v152
	ds_read_b128 v[156:159], v156
	s_add_u32 s24, s90, 0xb0000
	s_addc_u32 s25, s91, 0
	s_mov_b32 m0, s53
	v_lshl_add_u64 v[198:199], s[24:25], 0, v[130:131]
	ds_read_b128 v[166:169], v145 offset:32768
	ds_read_b128 v[170:173], v145 offset:33792
	ds_read_b128 v[174:177], v145 offset:34816
	ds_read_b128 v[178:181], v145 offset:35840
	ds_read_b128 v[182:185], v145 offset:36864
	ds_read_b128 v[186:189], v145 offset:37888
	ds_read_b128 v[190:193], v145 offset:38912
	ds_read_b128 v[194:197], v145 offset:39936
	global_load_lds_dwordx4 v[198:199], off
	v_lshl_add_u64 v[198:199], s[24:25], 0, v[132:133]
	s_mov_b32 m0, s58
	s_nop 0
	global_load_lds_dwordx4 v[198:199], off
	s_barrier
	s_waitcnt lgkmcnt(0)
	s_waitcnt lgkmcnt(0)
	v_mfma_f32_16x16x32_bf16 v[126:129], v[140:143], v[166:169], v[126:129]
	v_mfma_f32_16x16x32_bf16 v[122:125], v[152:155], v[166:169], v[122:125]
	v_mfma_f32_16x16x32_bf16 v[110:113], v[140:143], v[174:177], v[110:113]
	v_mfma_f32_16x16x32_bf16 v[106:109], v[152:155], v[174:177], v[106:109]
	v_mfma_f32_16x16x32_bf16 v[94:97], v[140:143], v[182:185], v[94:97]
	v_mfma_f32_16x16x32_bf16 v[90:93], v[152:155], v[182:185], v[90:93]
	v_mfma_f32_16x16x32_bf16 v[78:81], v[140:143], v[190:193], v[78:81]
	v_mfma_f32_16x16x32_bf16 v[74:77], v[152:155], v[190:193], v[74:77]
	v_mfma_f32_16x16x32_bf16 v[126:129], v[148:151], v[170:173], v[126:129]
	v_mfma_f32_16x16x32_bf16 v[122:125], v[156:159], v[170:173], v[122:125]
	v_mfma_f32_16x16x32_bf16 v[110:113], v[148:151], v[178:181], v[110:113]
	v_mfma_f32_16x16x32_bf16 v[106:109], v[156:159], v[178:181], v[106:109]
	v_mfma_f32_16x16x32_bf16 v[94:97], v[148:151], v[186:189], v[94:97]
	v_mfma_f32_16x16x32_bf16 v[90:93], v[156:159], v[186:189], v[90:93]
	v_mfma_f32_16x16x32_bf16 v[78:81], v[148:151], v[194:197], v[78:81]
	v_mfma_f32_16x16x32_bf16 v[74:77], v[156:159], v[194:197], v[74:77]
	s_barrier
	v_or_b32_e32 v163, 0x1c000, v146
	s_mov_b32 m0, s59
	v_add_u32_e32 v165, 0x1c400, v146
	ds_read_b128 v[198:201], v163
	ds_read_b128 v[202:205], v165
	v_add_u32_e32 v163, 0x1c800, v146
	v_lshl_add_u64 v[160:161], v[160:161], 0, s[10:11]
	v_add_u32_e32 v165, 0x1cc00, v146
	ds_read_b128 v[206:209], v163
	ds_read_b128 v[210:213], v165
	global_load_lds_dwordx4 v[160:161], off
	v_lshl_add_u64 v[160:161], v[214:215], 0, s[10:11]
	s_mov_b32 m0, s60
	s_nop 0
	global_load_lds_dwordx4 v[160:161], off
	s_barrier
	s_waitcnt lgkmcnt(0)
	s_waitcnt lgkmcnt(0)
	v_mfma_f32_16x16x32_bf16 v[118:121], v[198:201], v[166:169], v[118:121]
	v_mfma_f32_16x16x32_bf16 v[114:117], v[206:209], v[166:169], v[114:117]
	v_mfma_f32_16x16x32_bf16 v[102:105], v[198:201], v[174:177], v[102:105]
	v_mfma_f32_16x16x32_bf16 v[98:101], v[206:209], v[174:177], v[98:101]
	v_mfma_f32_16x16x32_bf16 v[86:89], v[198:201], v[182:185], v[86:89]
	v_mfma_f32_16x16x32_bf16 v[82:85], v[206:209], v[182:185], v[82:85]
	v_mfma_f32_16x16x32_bf16 v[70:73], v[198:201], v[190:193], v[70:73]
	v_mfma_f32_16x16x32_bf16 v[66:69], v[206:209], v[190:193], v[66:69]
	v_mfma_f32_16x16x32_bf16 v[118:121], v[202:205], v[170:173], v[118:121]
	v_mfma_f32_16x16x32_bf16 v[114:117], v[210:213], v[170:173], v[114:117]
	v_mfma_f32_16x16x32_bf16 v[102:105], v[202:205], v[178:181], v[102:105]
	v_mfma_f32_16x16x32_bf16 v[98:101], v[210:213], v[178:181], v[98:101]
	v_mfma_f32_16x16x32_bf16 v[86:89], v[202:205], v[186:189], v[86:89]
	v_mfma_f32_16x16x32_bf16 v[82:85], v[210:213], v[186:189], v[82:85]
	v_mfma_f32_16x16x32_bf16 v[70:73], v[202:205], v[194:197], v[70:73]
	v_mfma_f32_16x16x32_bf16 v[66:69], v[210:213], v[194:197], v[66:69]
	s_mov_b32 m0, s62
	v_lshl_add_u64 v[160:161], v[216:217], 0, s[10:11]
	s_barrier
	ds_read_b128 v[166:169], v145 offset:49152
	ds_read_b128 v[170:173], v145 offset:50176
	ds_read_b128 v[174:177], v145 offset:51200
	ds_read_b128 v[178:181], v145 offset:52224
	ds_read_b128 v[182:185], v145 offset:53248
	ds_read_b128 v[186:189], v145 offset:54272
	ds_read_b128 v[190:193], v145 offset:55296
	ds_read_b128 v[194:197], v145 offset:56320
	global_load_lds_dwordx4 v[160:161], off
	v_lshl_add_u64 v[160:161], v[218:219], 0, s[10:11]
	s_mov_b32 m0, s72
	s_nop 0
	global_load_lds_dwordx4 v[160:161], off
	s_barrier
; DI bf16_t f2bf(float x) { unsigned u = __float_as_uint(x); u += 0x7fffu + ((u >> 16) & 1u); return (bf16_t)(u >> 16); }
; DI unsigned pack2(float lo, float hi) { f32x2_t v = {lo, hi}; return __builtin_bit_cast(unsigned, __builtin_convertvector(v, bf16x2_t)); }
; #define PG8_LAS __attribute__((address_space(3)))
; #define PG8_STAGE(bufoff, gbase, voff) do { _Pragma("unroll") for (int _i = 0; _i < 2; ++_i) \
;     __builtin_amdgcn_global_load_lds((const unsigned*)((const char*)(gbase) + (voff)[_i]), (PG8_LAS unsigned*)(lds + (bufoff) + ldsw + _i * 8192), 16, 0, 0); } while (0)
; #define PG8_WAIT_V(n) asm volatile("s_waitcnt vmcnt(" #n ")" ::: "memory")
; #define PG8_WAIT_L(n) asm volatile("s_waitcnt lgkmcnt(" #n ")" ::: "memory")
; #define PG8_BAR __builtin_amdgcn_s_barrier()
; #define PG8_SCHED __builtin_amdgcn_sched_barrier(0)
;   DI void operator()(const f32x4 (&acc)[2][2][4][2], const Unit& u, int wr, int wc, int fr, int fq, const PG8_LAS float*) const {
;     const int row0 = u.pm * BM + wr * 64 + fr, col0 = u.pn * BM + wc * 32 + 8 * fq;
; #pragma unroll
;     for (int ai = 0; ai < 2; ++ai)
; #pragma unroll
;       for (int m = 0; m < 4; ++m) { const int row = row0 + ai * HALF + m * 16; bf16_t* rowp = dst + (size_t)row * DM + col0; float ss = 0.f;
; #pragma unroll
;         for (int bj = 0; bj < 2; ++bj) { const f32x4 v0 = acc[ai][bj][m][0] * coef, v1 = acc[ai][bj][m][1] * coef;
;           ss += v0[0] * v0[0] + v0[1] * v0[1] + v0[2] * v0[2] + v0[3] * v0[3] + v1[0] * v1[0] + v1[1] * v1[1] + v1[2] * v1[2] + v1[3] * v1[3];
;           u32x4 w; w.x = pack2(v0[0], v0[1]); w.y = pack2(v0[2], v0[3]); w.z = pack2(v1[0], v1[1]); w.w = pack2(v1[2], v1[3]);
;           *(u32x4*)(rowp + bj * HALF) = w; }
;         ss += __shfl_xor(ss, 16); ss += __shfl_xor(ss, 32);
;         if (fq == 0) ssq[(size_t)row * 16 + u.pn * 4 + wc] = f2bf(ss); }
; template <class Epi>
; DI void gemm_phase(const bf16_t* __restrict__ gA, const bf16_t* __restrict__ gBt, int M, int N, int K, const Epi& E, char* lds_generic) {
;     ...
;       PG8_BAR; PG8_WAIT_L(0); PG8_MMA(1, 0, At, B0); PG8_BAR; PG8_SCHED;
;       PG8_STAGE(PG8_SB(1, 1), b3 + hstep, voffB);
;       PG8_WAIT_V(6); PG8_BAR; PG8_MMA(1, 1, At, B1); PG8_BAR;
;     }
;     uint4 rtn_ = {0u, 0u, 0u, 0u};
;     if (has_next) PG8_RTAB_LOAD(rtn_, nxt);
;     E(acc, cur, wr, wc, fr, fq, (const PG8_LAS float*)(lds + RT_OFF) + (ui & 1) * 256);
	s_waitcnt lgkmcnt(0)
	s_waitcnt lgkmcnt(0)
	v_mfma_f32_16x16x32_bf16 v[62:65], v[140:143], v[166:169], v[62:65]
	v_mfma_f32_16x16x32_bf16 v[58:61], v[152:155], v[166:169], v[58:61]
	v_mfma_f32_16x16x32_bf16 v[46:49], v[140:143], v[174:177], v[46:49]
	v_mfma_f32_16x16x32_bf16 v[42:45], v[152:155], v[174:177], v[42:45]
	v_mfma_f32_16x16x32_bf16 v[30:33], v[140:143], v[182:185], v[30:33]
	v_mfma_f32_16x16x32_bf16 v[26:29], v[152:155], v[182:185], v[26:29]
	v_mfma_f32_16x16x32_bf16 v[14:17], v[140:143], v[190:193], v[14:17]
	v_mfma_f32_16x16x32_bf16 v[10:13], v[152:155], v[190:193], v[10:13]
	v_mfma_f32_16x16x32_bf16 v[62:65], v[148:151], v[170:173], v[62:65]
	v_mfma_f32_16x16x32_bf16 v[58:61], v[156:159], v[170:173], v[58:61]
	v_mfma_f32_16x16x32_bf16 v[46:49], v[148:151], v[178:181], v[46:49]
	v_mfma_f32_16x16x32_bf16 v[42:45], v[156:159], v[178:181], v[42:45]
	v_mfma_f32_16x16x32_bf16 v[30:33], v[148:151], v[186:189], v[30:33]
	v_mfma_f32_16x16x32_bf16 v[26:29], v[156:159], v[186:189], v[26:29]
	v_mfma_f32_16x16x32_bf16 v[14:17], v[148:151], v[194:197], v[14:17]
	v_mfma_f32_16x16x32_bf16 v[10:13], v[156:159], v[194:197], v[10:13]
	s_barrier
	s_add_u32 s24, s30, 0xb0080
	s_addc_u32 s25, s31, 0
	s_mov_b32 m0, s74
	v_lshl_add_u64 v[140:141], s[24:25], 0, v[0:1]
	global_load_lds_dwordx4 v[140:141], off
	v_lshl_add_u64 v[140:141], s[24:25], 0, v[134:135]
	s_mov_b32 m0, s19
	s_nop 0
	global_load_lds_dwordx4 v[140:141], off
	s_waitcnt vmcnt(6)
	s_barrier
	v_mfma_f32_16x16x32_bf16 v[54:57], v[198:201], v[166:169], v[54:57]
	v_mfma_f32_16x16x32_bf16 v[50:53], v[206:209], v[166:169], v[50:53]
	v_mfma_f32_16x16x32_bf16 v[38:41], v[198:201], v[174:177], v[38:41]
	v_mfma_f32_16x16x32_bf16 v[34:37], v[206:209], v[174:177], v[34:37]
	v_mfma_f32_16x16x32_bf16 v[22:25], v[198:201], v[182:185], v[22:25]
	v_mfma_f32_16x16x32_bf16 v[18:21], v[206:209], v[182:185], v[18:21]
	v_mfma_f32_16x16x32_bf16 v[6:9], v[198:201], v[190:193], v[6:9]
	v_mfma_f32_16x16x32_bf16 v[2:5], v[206:209], v[190:193], v[2:5]
	v_mfma_f32_16x16x32_bf16 v[54:57], v[202:205], v[170:173], v[54:57]
	v_mfma_f32_16x16x32_bf16 v[50:53], v[210:213], v[170:173], v[50:53]
	v_mfma_f32_16x16x32_bf16 v[38:41], v[202:205], v[178:181], v[38:41]
	v_mfma_f32_16x16x32_bf16 v[34:37], v[210:213], v[178:181], v[34:37]
	v_mfma_f32_16x16x32_bf16 v[22:25], v[202:205], v[186:189], v[22:25]
	v_mfma_f32_16x16x32_bf16 v[18:21], v[210:213], v[186:189], v[18:21]
	v_mfma_f32_16x16x32_bf16 v[6:9], v[202:205], v[194:197], v[6:9]
	v_mfma_f32_16x16x32_bf16 v[2:5], v[210:213], v[194:197], v[2:5]
	s_add_i32 s23, s23, 2
	s_add_u32 s21, s21, 0x100
	s_addc_u32 s22, s22, 0
	s_cmp_gt_u32 s23, 41
	s_mov_b64 s[88:89], s[28:29]
	s_barrier
	s_cbranch_scc0 .LBB0_684
	v_pk_mul_f32 v[126:127], v[126:127], 0.5 op_sel_hi:[1,0]
	v_pk_mul_f32 v[128:129], v[128:129], 0.5 op_sel_hi:[1,0]
	v_mul_f32_e32 v154, v127, v127
	v_fmac_f32_e32 v154, v126, v126
	v_fmac_f32_e32 v154, v128, v128
	v_pk_mul_f32 v[118:119], v[118:119], 0.5 op_sel_hi:[1,0]
	v_pk_mul_f32 v[152:153], v[124:125], 0.5 op_sel_hi:[1,0]
	v_pk_mul_f32 v[124:125], v[122:123], 0.5 op_sel_hi:[1,0]
	v_fmac_f32_e32 v154, v129, v129
	v_cvt_pk_bf16_f32 v123, v128, v129
	v_pk_mul_f32 v[128:129], v[114:115], 0.5 op_sel_hi:[1,0]
	v_mul_f32_e32 v114, v119, v119
	v_pk_mul_f32 v[120:121], v[120:121], 0.5 op_sel_hi:[1,0]
	v_fmac_f32_e32 v114, v118, v118
	v_fmac_f32_e32 v114, v120, v120
	v_fmac_f32_e32 v114, v121, v121
	v_fmac_f32_e32 v154, v124, v124
	v_fmac_f32_e32 v114, v128, v128
	v_xor_b32_e32 v143, 16, v223
	v_fmac_f32_e32 v154, v125, v125
	v_cvt_pk_bf16_f32 v122, v126, v127
	v_pk_mul_f32 v[126:127], v[116:117], 0.5 op_sel_hi:[1,0]
	v_fmac_f32_e32 v114, v129, v129
	v_cmp_lt_i32_e32 vcc, v143, v225
	v_fmac_f32_e32 v154, v152, v152
	v_fmac_f32_e32 v114, v126, v126
	v_cndmask_b32_e32 v143, v223, v143, vcc
	v_fmac_f32_e32 v154, v153, v153
	v_fmac_f32_e32 v114, v127, v127
	v_lshlrev_b32_e32 v149, 2, v143
	v_add_f32_e32 v114, v154, v114
	ds_bpermute_b32 v115, v149, v114
	v_xor_b32_e32 v143, 32, v223
	v_cmp_lt_i32_e32 vcc, v143, v225
	v_lshl_add_u32 v142, s9, 8, v144
	v_lshl_or_b32 v140, s76, 8, v147
	v_cndmask_b32_e32 v143, v223, v143, vcc
	v_lshlrev_b32_e32 v148, 2, v143
	s_waitcnt lgkmcnt(0)
	v_add_f32_e32 v114, v114, v115
	ds_bpermute_b32 v115, v148, v114
	v_ashrrev_i32_e32 v143, 31, v142
	v_lshlrev_b64 v[150:151], 11, v[142:143]
	v_ashrrev_i32_e32 v141, 31, v140
	s_lshl_b32 s28, s76, 2
	v_lshl_add_u64 v[150:151], s[26:27], 0, v[150:151]
	s_ashr_i32 s29, s28, 31
	v_lshl_add_u64 v[150:151], v[140:141], 1, v[150:151]
	v_cvt_pk_bf16_f32 v124, v124, v125
	v_cvt_pk_bf16_f32 v125, v152, v153
	v_cvt_pk_bf16_f32 v116, v118, v119
	v_cvt_pk_bf16_f32 v117, v120, v121
	v_cvt_pk_bf16_f32 v118, v128, v129
	v_cvt_pk_bf16_f32 v119, v126, v127
	global_store_dwordx4 v[150:151], v[122:125], off
	global_store_dwordx4 v[150:151], v[116:119], off offset:256
	s_and_saveexec_b64 s[30:31], s[36:37]
	s_cbranch_execz .LBB0_687
	s_waitcnt lgkmcnt(0)
	v_add_f32_e32 v114, v114, v115
	v_bfe_u32 v115, v114, 16, 1
	v_add3_u32 v116, v114, v115, s63
	v_lshlrev_b64 v[114:115], 5, v[142:143]
	v_lshl_add_u64 v[114:115], s[84:85], 0, v[114:115]
	v_lshl_add_u64 v[114:115], s[28:29], 1, v[114:115]
	s_lshl_b32 s76, s7, 1
	v_lshl_add_u64 v[114:115], v[114:115], 0, s[76:77]
	global_store_short_d16_hi v[114:115], v116, off
